# v8 with every s_setprio removed from the six GEMM K-loops (A/B of the priority flips)
# baseline (speedup 1.0000x reference)
; #define PG8_STAGE(bufoff, gbase, voff) do { _Pragma("unroll") for (int _i = 0; _i < 2; ++_i) \
;         __builtin_amdgcn_global_load_lds((const unsigned*)((const char*)(gbase) + (voff)[_i]), (LAS unsigned*)(lds + (bufoff) + ldsw + _i * 8192), 16, 0, 0); } while (0)
; #define PG8_LDA(dst, b, h) do { _Pragma("unroll") for (int m = 0; m < 4; ++m) _Pragma("unroll") for (int k = 0; k < 2; ++k) dst[m][k] = *(const LAS bf16x8*)(lds + PG8_SA(b, h) + aoff + m * 2048 + k * KOFF); } while (0)
; #define PG8_LDB(dst, b, h) do { _Pragma("unroll") for (int n = 0; n < 2; ++n) _Pragma("unroll") for (int k = 0; k < 2; ++k) dst[n][k] = *(const LAS bf16x8*)(lds + PG8_SB(b, h) + boff + n * 2048 + k * KOFF); } while (0)
; #define PG8_WAIT_V(n) asm volatile("s_waitcnt vmcnt(" #n ")" ::: "memory")
; #define PG8_WAIT_L(n) asm volatile("s_waitcnt lgkmcnt(" #n ")" ::: "memory")
; #define PG8_BAR __builtin_amdgcn_s_barrier()
; #define PG8_SCHED __builtin_amdgcn_sched_barrier(0)
; template <class Epi, bool ALIGN_EPI = true, bool FP8 = false>
; __device__ __forceinline__ void gemm_phase(LAS unsigned char* lds, const Gemm g, const StaticOrder& S, const Epi& E, const int wid) {
;     ...
;             const char* a1 = cA + (size_t)(t + 1) * kstep;
;             const char* a2 = last ? nA : cA + (size_t)(t + 2) * kstep; const char* b2 = last ? nB : cB + (size_t)(t + 2) * kstep;
;             const char* a3 = a2 + kstep; const char* b3 = b2 + kstep;
;             PG8_LDB(B0, 0, 0); PG8_LDB(B1, 0, 1); PG8_SCHED; PG8_LDA(At, 0, 0); PG8_STAGE(PG8_SA(1, 1), a1 + hstep, voffA);
;             PG8_WAIT_V(8); PG8_WAIT_L(0); PG8_BAR; PG8_MMA(0, 0, At, B0); PG8_MMA(0, 1, At, B1); PG8_BAR; PG8_SCHED;
;             PG8_LDA(At, 0, 1); PG8_STAGE(PG8_SB(0, 0), b2, voffB); PG8_STAGE(PG8_SB(0, 1), b2 + hstep, voffB); PG8_STAGE(PG8_SA(0, 0), a2, voffA);
;             PG8_WAIT_V(8); PG8_WAIT_L(0); PG8_BAR; PG8_MMA(1, 0, At, B0); PG8_MMA(1, 1, At, B1); PG8_BAR; PG8_SCHED;
.LBB0_506:
	ds_read_b128 v[146:149], v137
	ds_read_b128 v[154:157], v137 offset:1024
	ds_read_b128 v[158:161], v137 offset:2048
	ds_read_b128 v[162:165], v137 offset:3072
	ds_read_b128 v[166:169], v152
	ds_read_b128 v[170:173], v152 offset:1024
	ds_read_b128 v[174:177], v152 offset:2048
	ds_read_b128 v[178:181], v152 offset:3072
	s_add_i32 s52, s34, 2
	s_add_u32 s35, s30, 0xfff80080
	s_addc_u32 s36, s31, -1
	s_cmp_eq_u32 s39, s34
	s_cselect_b32 s34, s38, s42
	s_cselect_b32 s37, s3, s36
	s_cselect_b32 s36, s23, s35
	s_cselect_b32 s35, s25, s43
	v_lshl_add_u64 v[214:215], s[30:31], 0, v[140:141]
	s_add_i32 m0, s75, 0xc000
	ds_read_b128 v[182:185], v153
	ds_read_b128 v[186:189], v153 offset:1024
	ds_read_b128 v[190:193], v153 offset:2048
	ds_read_b128 v[194:197], v153 offset:3072
	ds_read_b128 v[198:201], v153 offset:4096
	ds_read_b128 v[202:205], v153 offset:5120
	ds_read_b128 v[206:209], v153 offset:6144
	ds_read_b128 v[210:213], v153 offset:7168
	global_load_lds_dwordx4 v[214:215], off
	v_lshl_add_u64 v[214:215], s[30:31], 0, v[142:143]
	s_add_i32 m0, s75, 0xe000
	s_nop 0
	global_load_lds_dwordx4 v[214:215], off
	s_waitcnt vmcnt(8) lgkmcnt(0)
	s_barrier
	v_mfma_f32_16x16x32_bf16 v[124:127], v[146:149], v[182:185], v[124:127]
	v_mfma_f32_16x16x32_bf16 v[120:123], v[158:161], v[182:185], v[120:123]
	v_mfma_f32_16x16x32_bf16 v[108:111], v[146:149], v[190:193], v[108:111]
	v_mfma_f32_16x16x32_bf16 v[104:107], v[158:161], v[190:193], v[104:107]
	v_mfma_f32_16x16x32_bf16 v[92:95], v[146:149], v[198:201], v[92:95]
	v_mfma_f32_16x16x32_bf16 v[88:91], v[158:161], v[198:201], v[88:91]
	v_mfma_f32_16x16x32_bf16 v[76:79], v[146:149], v[206:209], v[76:79]
	v_mfma_f32_16x16x32_bf16 v[72:75], v[158:161], v[206:209], v[72:75]
	v_mfma_f32_16x16x32_bf16 v[124:127], v[154:157], v[186:189], v[124:127]
	v_mfma_f32_16x16x32_bf16 v[120:123], v[162:165], v[186:189], v[120:123]
	v_mfma_f32_16x16x32_bf16 v[108:111], v[154:157], v[194:197], v[108:111]
	v_mfma_f32_16x16x32_bf16 v[104:107], v[162:165], v[194:197], v[104:107]
	v_mfma_f32_16x16x32_bf16 v[92:95], v[154:157], v[202:205], v[92:95]
	v_mfma_f32_16x16x32_bf16 v[88:91], v[162:165], v[202:205], v[88:91]
	v_mfma_f32_16x16x32_bf16 v[76:79], v[154:157], v[210:213], v[76:79]
	v_mfma_f32_16x16x32_bf16 v[72:75], v[162:165], v[210:213], v[72:75]
	v_mfma_f32_16x16x32_bf16 v[116:119], v[166:169], v[182:185], v[116:119]
	v_mfma_f32_16x16x32_bf16 v[112:115], v[174:177], v[182:185], v[112:115]
	v_mfma_f32_16x16x32_bf16 v[100:103], v[166:169], v[190:193], v[100:103]
	v_mfma_f32_16x16x32_bf16 v[96:99], v[174:177], v[190:193], v[96:99]
	v_mfma_f32_16x16x32_bf16 v[84:87], v[166:169], v[198:201], v[84:87]
	v_mfma_f32_16x16x32_bf16 v[80:83], v[174:177], v[198:201], v[80:83]
	v_mfma_f32_16x16x32_bf16 v[68:71], v[166:169], v[206:209], v[68:71]
	v_mfma_f32_16x16x32_bf16 v[64:67], v[174:177], v[206:209], v[64:67]
	v_mfma_f32_16x16x32_bf16 v[116:119], v[170:173], v[186:189], v[116:119]
	v_mfma_f32_16x16x32_bf16 v[112:115], v[178:181], v[186:189], v[112:115]
	v_mfma_f32_16x16x32_bf16 v[100:103], v[170:173], v[194:197], v[100:103]
	v_mfma_f32_16x16x32_bf16 v[96:99], v[178:181], v[194:197], v[96:99]
	v_mfma_f32_16x16x32_bf16 v[84:87], v[170:173], v[202:205], v[84:87]
	v_mfma_f32_16x16x32_bf16 v[80:83], v[178:181], v[202:205], v[80:83]
	v_mfma_f32_16x16x32_bf16 v[68:71], v[170:173], v[210:213], v[68:71]
	v_mfma_f32_16x16x32_bf16 v[64:67], v[178:181], v[210:213], v[64:67]
	s_barrier
	s_add_i32 s54, s86, s48
	v_lshl_add_u64 v[214:215], s[34:35], 0, v[132:133]
	s_mov_b32 m0, s54
	ds_read_b128 v[182:185], v153 offset:16384
	ds_read_b128 v[186:189], v153 offset:17408
	ds_read_b128 v[190:193], v153 offset:18432
	ds_read_b128 v[194:197], v153 offset:19456
	ds_read_b128 v[198:201], v153 offset:20480
	ds_read_b128 v[202:205], v153 offset:21504
	ds_read_b128 v[206:209], v153 offset:22528
	ds_read_b128 v[210:213], v153 offset:23552
	global_load_lds_dwordx4 v[214:215], off
	s_add_i32 m0, s54, 0x2000
	s_add_u32 s64, s34, 0x80000
	v_lshl_add_u64 v[216:217], s[34:35], 0, v[128:129]
	s_addc_u32 s65, s35, 0
	s_add_i32 s54, s87, s48
	global_load_lds_dwordx4 v[216:217], off
	v_lshl_add_u64 v[218:219], s[64:65], 0, v[132:133]
	s_mov_b32 m0, s54
	v_lshl_add_u64 v[220:221], s[36:37], 0, v[130:131]
	global_load_lds_dwordx4 v[218:219], off
	v_lshl_add_u64 v[218:219], s[64:65], 0, v[128:129]
	s_add_i32 m0, s54, 0x2000
	s_nop 0
	global_load_lds_dwordx4 v[218:219], off
	v_lshl_add_u64 v[218:219], s[36:37], 0, v[134:135]
	s_mov_b32 m0, s75
	s_nop 0
	global_load_lds_dwordx4 v[218:219], off
	s_mov_b32 m0, s76
	s_nop 0
	global_load_lds_dwordx4 v[220:221], off
	s_waitcnt vmcnt(8) lgkmcnt(0)
	s_barrier
; #define PG8_STAGE(bufoff, gbase, voff) do { _Pragma("unroll") for (int _i = 0; _i < 2; ++_i) \
;         __builtin_amdgcn_global_load_lds((const unsigned*)((const char*)(gbase) + (voff)[_i]), (LAS unsigned*)(lds + (bufoff) + ldsw + _i * 8192), 16, 0, 0); } while (0)
; #define PG8_LDA(dst, b, h) do { _Pragma("unroll") for (int m = 0; m < 4; ++m) _Pragma("unroll") for (int k = 0; k < 2; ++k) dst[m][k] = *(const LAS bf16x8*)(lds + PG8_SA(b, h) + aoff + m * 2048 + k * KOFF); } while (0)
; #define PG8_LDB(dst, b, h) do { _Pragma("unroll") for (int n = 0; n < 2; ++n) _Pragma("unroll") for (int k = 0; k < 2; ++k) dst[n][k] = *(const LAS bf16x8*)(lds + PG8_SB(b, h) + boff + n * 2048 + k * KOFF); } while (0)
; #define PG8_WAIT_V(n) asm volatile("s_waitcnt vmcnt(" #n ")" ::: "memory")
; #define PG8_WAIT_L(n) asm volatile("s_waitcnt lgkmcnt(" #n ")" ::: "memory")
; #define PG8_BAR __builtin_amdgcn_s_barrier()
; #define PG8_SCHED __builtin_amdgcn_sched_barrier(0)
; template <class Epi, bool ALIGN_EPI = true, bool FP8 = false>
; __device__ __forceinline__ void gemm_phase(LAS unsigned char* lds, const Gemm g, const StaticOrder& S, const Epi& E, const int wid) {
;     ...
;             PG8_WAIT_V(8); PG8_WAIT_L(0); PG8_BAR; PG8_MMA(1, 0, At, B0); PG8_MMA(1, 1, At, B1); PG8_BAR; PG8_SCHED;
;             PG8_LDB(B0, 1, 0); PG8_LDB(B1, 1, 1); PG8_SCHED; PG8_LDA(At, 1, 0); PG8_STAGE(PG8_SA(0, 1), a2 + hstep, voffA);
;             PG8_WAIT_V(8); PG8_WAIT_L(0); PG8_BAR; PG8_MMA(0, 0, At, B0); PG8_MMA(0, 1, At, B1); PG8_BAR; PG8_SCHED;
	v_mfma_f32_16x16x32_bf16 v[60:63], v[146:149], v[182:185], v[60:63]
	v_mfma_f32_16x16x32_bf16 v[56:59], v[158:161], v[182:185], v[56:59]
	v_mfma_f32_16x16x32_bf16 v[44:47], v[146:149], v[190:193], v[44:47]
	v_mfma_f32_16x16x32_bf16 v[40:43], v[158:161], v[190:193], v[40:43]
	v_mfma_f32_16x16x32_bf16 v[28:31], v[146:149], v[198:201], v[28:31]
	v_mfma_f32_16x16x32_bf16 v[24:27], v[158:161], v[198:201], v[24:27]
	v_mfma_f32_16x16x32_bf16 v[12:15], v[146:149], v[206:209], v[12:15]
	v_mfma_f32_16x16x32_bf16 v[8:11], v[158:161], v[206:209], v[8:11]
	v_mfma_f32_16x16x32_bf16 v[60:63], v[154:157], v[186:189], v[60:63]
	v_mfma_f32_16x16x32_bf16 v[56:59], v[162:165], v[186:189], v[56:59]
	v_mfma_f32_16x16x32_bf16 v[44:47], v[154:157], v[194:197], v[44:47]
	v_mfma_f32_16x16x32_bf16 v[40:43], v[162:165], v[194:197], v[40:43]
	v_mfma_f32_16x16x32_bf16 v[28:31], v[154:157], v[202:205], v[28:31]
	v_mfma_f32_16x16x32_bf16 v[24:27], v[162:165], v[202:205], v[24:27]
	v_mfma_f32_16x16x32_bf16 v[12:15], v[154:157], v[210:213], v[12:15]
	v_mfma_f32_16x16x32_bf16 v[8:11], v[162:165], v[210:213], v[8:11]
	v_mfma_f32_16x16x32_bf16 v[52:55], v[166:169], v[182:185], v[52:55]
	v_mfma_f32_16x16x32_bf16 v[48:51], v[174:177], v[182:185], v[48:51]
	v_mfma_f32_16x16x32_bf16 v[36:39], v[166:169], v[190:193], v[36:39]
	v_mfma_f32_16x16x32_bf16 v[32:35], v[174:177], v[190:193], v[32:35]
	v_mfma_f32_16x16x32_bf16 v[20:23], v[166:169], v[198:201], v[20:23]
	v_mfma_f32_16x16x32_bf16 v[16:19], v[174:177], v[198:201], v[16:19]
	v_mfma_f32_16x16x32_bf16 v[4:7], v[166:169], v[206:209], v[4:7]
	v_mfma_f32_16x16x32_bf16 v[0:3], v[174:177], v[206:209], v[0:3]
	v_mfma_f32_16x16x32_bf16 v[52:55], v[170:173], v[186:189], v[52:55]
	v_mfma_f32_16x16x32_bf16 v[48:51], v[178:181], v[186:189], v[48:51]
	v_mfma_f32_16x16x32_bf16 v[36:39], v[170:173], v[194:197], v[36:39]
	v_mfma_f32_16x16x32_bf16 v[32:35], v[178:181], v[194:197], v[32:35]
	v_mfma_f32_16x16x32_bf16 v[20:23], v[170:173], v[202:205], v[20:23]
	v_mfma_f32_16x16x32_bf16 v[16:19], v[178:181], v[202:205], v[16:19]
	v_mfma_f32_16x16x32_bf16 v[4:7], v[170:173], v[210:213], v[4:7]
	v_mfma_f32_16x16x32_bf16 v[0:3], v[178:181], v[210:213], v[0:3]
	s_barrier
	s_add_i32 s54, 0, 0x18000
	s_add_i32 s64, 0, 0x1c000
	v_add_u32_e32 v162, s54, v150
	v_add_u32_e32 v178, s64, v150
	ds_read_b128 v[146:149], v162
	ds_read_b128 v[154:157], v162 offset:1024
	ds_read_b128 v[158:161], v162 offset:2048
	ds_read_b128 v[162:165], v162 offset:3072
	ds_read_b128 v[166:169], v178
	ds_read_b128 v[170:173], v178 offset:1024
	ds_read_b128 v[174:177], v178 offset:2048
	ds_read_b128 v[178:181], v178 offset:3072
	s_add_u32 s36, s36, 0x80000
	s_addc_u32 s37, s37, 0
	s_mov_b32 m0, s77
	v_lshl_add_u64 v[222:223], s[36:37], 0, v[134:135]
	ds_read_b128 v[182:185], v153 offset:32768
	ds_read_b128 v[186:189], v153 offset:33792
	ds_read_b128 v[190:193], v153 offset:34816
	ds_read_b128 v[194:197], v153 offset:35840
	ds_read_b128 v[198:201], v153 offset:36864
	ds_read_b128 v[202:205], v153 offset:37888
	ds_read_b128 v[206:209], v153 offset:38912
	ds_read_b128 v[210:213], v153 offset:39936
	global_load_lds_dwordx4 v[222:223], off
	v_lshl_add_u64 v[222:223], s[36:37], 0, v[130:131]
	s_mov_b32 m0, s78
	s_nop 0
	global_load_lds_dwordx4 v[222:223], off
	s_waitcnt vmcnt(8) lgkmcnt(0)
	s_barrier
	v_mfma_f32_16x16x32_bf16 v[124:127], v[146:149], v[182:185], v[124:127]
	v_mfma_f32_16x16x32_bf16 v[120:123], v[158:161], v[182:185], v[120:123]
	v_mfma_f32_16x16x32_bf16 v[108:111], v[146:149], v[190:193], v[108:111]
	v_mfma_f32_16x16x32_bf16 v[104:107], v[158:161], v[190:193], v[104:107]
	v_mfma_f32_16x16x32_bf16 v[92:95], v[146:149], v[198:201], v[92:95]
	v_mfma_f32_16x16x32_bf16 v[88:91], v[158:161], v[198:201], v[88:91]
	v_mfma_f32_16x16x32_bf16 v[76:79], v[146:149], v[206:209], v[76:79]
	v_mfma_f32_16x16x32_bf16 v[72:75], v[158:161], v[206:209], v[72:75]
	v_mfma_f32_16x16x32_bf16 v[124:127], v[154:157], v[186:189], v[124:127]
	v_mfma_f32_16x16x32_bf16 v[120:123], v[162:165], v[186:189], v[120:123]
	v_mfma_f32_16x16x32_bf16 v[108:111], v[154:157], v[194:197], v[108:111]
	v_mfma_f32_16x16x32_bf16 v[104:107], v[162:165], v[194:197], v[104:107]
	v_mfma_f32_16x16x32_bf16 v[92:95], v[154:157], v[202:205], v[92:95]
	v_mfma_f32_16x16x32_bf16 v[88:91], v[162:165], v[202:205], v[88:91]
	v_mfma_f32_16x16x32_bf16 v[76:79], v[154:157], v[210:213], v[76:79]
	v_mfma_f32_16x16x32_bf16 v[72:75], v[162:165], v[210:213], v[72:75]
	v_mfma_f32_16x16x32_bf16 v[116:119], v[166:169], v[182:185], v[116:119]
	v_mfma_f32_16x16x32_bf16 v[112:115], v[174:177], v[182:185], v[112:115]
	v_mfma_f32_16x16x32_bf16 v[100:103], v[166:169], v[190:193], v[100:103]
	v_mfma_f32_16x16x32_bf16 v[96:99], v[174:177], v[190:193], v[96:99]
	v_mfma_f32_16x16x32_bf16 v[84:87], v[166:169], v[198:201], v[84:87]
	v_mfma_f32_16x16x32_bf16 v[80:83], v[174:177], v[198:201], v[80:83]
	v_mfma_f32_16x16x32_bf16 v[68:71], v[166:169], v[206:209], v[68:71]
	v_mfma_f32_16x16x32_bf16 v[64:67], v[174:177], v[206:209], v[64:67]
	v_mfma_f32_16x16x32_bf16 v[116:119], v[170:173], v[186:189], v[116:119]
	v_mfma_f32_16x16x32_bf16 v[112:115], v[178:181], v[186:189], v[112:115]
	v_mfma_f32_16x16x32_bf16 v[100:103], v[170:173], v[194:197], v[100:103]
	v_mfma_f32_16x16x32_bf16 v[96:99], v[178:181], v[194:197], v[96:99]
	v_mfma_f32_16x16x32_bf16 v[84:87], v[170:173], v[202:205], v[84:87]
	v_mfma_f32_16x16x32_bf16 v[80:83], v[178:181], v[202:205], v[80:83]
	v_mfma_f32_16x16x32_bf16 v[68:71], v[170:173], v[210:213], v[68:71]
	v_mfma_f32_16x16x32_bf16 v[64:67], v[178:181], v[210:213], v[64:67]
	s_barrier
; #define PG8_STAGE(bufoff, gbase, voff) do { _Pragma("unroll") for (int _i = 0; _i < 2; ++_i) \
;         __builtin_amdgcn_global_load_lds((const unsigned*)((const char*)(gbase) + (voff)[_i]), (LAS unsigned*)(lds + (bufoff) + ldsw + _i * 8192), 16, 0, 0); } while (0)
; #define PG8_LDA(dst, b, h) do { _Pragma("unroll") for (int m = 0; m < 4; ++m) _Pragma("unroll") for (int k = 0; k < 2; ++k) dst[m][k] = *(const LAS bf16x8*)(lds + PG8_SA(b, h) + aoff + m * 2048 + k * KOFF); } while (0)
; #define PG8_WAIT_V(n) asm volatile("s_waitcnt vmcnt(" #n ")" ::: "memory")
; #define PG8_WAIT_L(n) asm volatile("s_waitcnt lgkmcnt(" #n ")" ::: "memory")
; #define PG8_BAR __builtin_amdgcn_s_barrier()
; #define PG8_SCHED __builtin_amdgcn_sched_barrier(0)
; template <class Epi, bool ALIGN_EPI = true, bool FP8 = false>
; __device__ __forceinline__ void gemm_phase(LAS unsigned char* lds, const Gemm g, const StaticOrder& S, const Epi& E, const int wid) {
;     ...
;             PG8_LDA(At, 1, 1); PG8_STAGE(PG8_SB(1, 0), b3, voffB); PG8_STAGE(PG8_SB(1, 1), b3 + hstep, voffB); PG8_STAGE(PG8_SA(1, 0), a3, voffA);
;             PG8_WAIT_V(8); PG8_WAIT_L(0); PG8_BAR; PG8_MMA(1, 0, At, B0); PG8_MMA(1, 1, At, B1); PG8_BAR; PG8_SCHED;
;         }
	s_add_i32 s36, s54, s48
	v_lshl_add_u64 v[214:215], v[214:215], 0, s[16:17]
	s_mov_b32 m0, s36
	ds_read_b128 v[182:185], v153 offset:49152
	ds_read_b128 v[186:189], v153 offset:50176
	ds_read_b128 v[190:193], v153 offset:51200
	ds_read_b128 v[194:197], v153 offset:52224
	ds_read_b128 v[198:201], v153 offset:53248
	ds_read_b128 v[202:205], v153 offset:54272
	ds_read_b128 v[206:209], v153 offset:55296
	ds_read_b128 v[210:213], v153 offset:56320
	global_load_lds_dwordx4 v[214:215], off
	s_add_i32 m0, s36, 0x2000
	s_add_u32 s34, s34, 0x80080
	v_lshl_add_u64 v[214:215], v[216:217], 0, s[16:17]
	s_addc_u32 s35, s35, 0
	s_add_i32 s36, s64, s48
	global_load_lds_dwordx4 v[214:215], off
	v_lshl_add_u64 v[214:215], s[34:35], 0, v[132:133]
	s_mov_b32 m0, s36
	s_nop 0
	global_load_lds_dwordx4 v[214:215], off
	v_lshl_add_u64 v[214:215], s[34:35], 0, v[128:129]
	s_add_i32 m0, s36, 0x2000
	s_nop 0
	global_load_lds_dwordx4 v[214:215], off
	v_lshl_add_u64 v[214:215], v[218:219], 0, s[16:17]
	s_mov_b32 m0, s83
	s_nop 0
	global_load_lds_dwordx4 v[214:215], off
	v_lshl_add_u64 v[214:215], v[220:221], 0, s[16:17]
	s_mov_b32 m0, s84
	s_nop 0
	global_load_lds_dwordx4 v[214:215], off
	s_waitcnt vmcnt(8) lgkmcnt(0)
	s_barrier
	v_mfma_f32_16x16x32_bf16 v[60:63], v[146:149], v[182:185], v[60:63]
	v_mfma_f32_16x16x32_bf16 v[56:59], v[158:161], v[182:185], v[56:59]
	v_mfma_f32_16x16x32_bf16 v[44:47], v[146:149], v[190:193], v[44:47]
	v_mfma_f32_16x16x32_bf16 v[40:43], v[158:161], v[190:193], v[40:43]
	v_mfma_f32_16x16x32_bf16 v[28:31], v[146:149], v[198:201], v[28:31]
	v_mfma_f32_16x16x32_bf16 v[24:27], v[158:161], v[198:201], v[24:27]
	v_mfma_f32_16x16x32_bf16 v[12:15], v[146:149], v[206:209], v[12:15]
	v_mfma_f32_16x16x32_bf16 v[8:11], v[158:161], v[206:209], v[8:11]
	v_mfma_f32_16x16x32_bf16 v[60:63], v[154:157], v[186:189], v[60:63]
	v_mfma_f32_16x16x32_bf16 v[56:59], v[162:165], v[186:189], v[56:59]
	v_mfma_f32_16x16x32_bf16 v[44:47], v[154:157], v[194:197], v[44:47]
	v_mfma_f32_16x16x32_bf16 v[40:43], v[162:165], v[194:197], v[40:43]
	v_mfma_f32_16x16x32_bf16 v[28:31], v[154:157], v[202:205], v[28:31]
	v_mfma_f32_16x16x32_bf16 v[24:27], v[162:165], v[202:205], v[24:27]
	v_mfma_f32_16x16x32_bf16 v[12:15], v[154:157], v[210:213], v[12:15]
	v_mfma_f32_16x16x32_bf16 v[8:11], v[162:165], v[210:213], v[8:11]
	v_mfma_f32_16x16x32_bf16 v[52:55], v[166:169], v[182:185], v[52:55]
	v_mfma_f32_16x16x32_bf16 v[48:51], v[174:177], v[182:185], v[48:51]
	v_mfma_f32_16x16x32_bf16 v[36:39], v[166:169], v[190:193], v[36:39]
	v_mfma_f32_16x16x32_bf16 v[32:35], v[174:177], v[190:193], v[32:35]
	v_mfma_f32_16x16x32_bf16 v[20:23], v[166:169], v[198:201], v[20:23]
	v_mfma_f32_16x16x32_bf16 v[16:19], v[174:177], v[198:201], v[16:19]
	v_mfma_f32_16x16x32_bf16 v[4:7], v[166:169], v[206:209], v[4:7]
	v_mfma_f32_16x16x32_bf16 v[0:3], v[174:177], v[206:209], v[0:3]
	v_mfma_f32_16x16x32_bf16 v[52:55], v[170:173], v[186:189], v[52:55]
	v_mfma_f32_16x16x32_bf16 v[48:51], v[178:181], v[186:189], v[48:51]
	v_mfma_f32_16x16x32_bf16 v[36:39], v[170:173], v[194:197], v[36:39]
	v_mfma_f32_16x16x32_bf16 v[32:35], v[178:181], v[194:197], v[32:35]
	v_mfma_f32_16x16x32_bf16 v[20:23], v[170:173], v[202:205], v[20:23]
	v_mfma_f32_16x16x32_bf16 v[16:19], v[178:181], v[202:205], v[16:19]
	v_mfma_f32_16x16x32_bf16 v[4:7], v[170:173], v[210:213], v[4:7]
	v_mfma_f32_16x16x32_bf16 v[0:3], v[178:181], v[210:213], v[0:3]
	s_barrier
	s_add_u32 s30, s30, 0x100
	s_addc_u32 s31, s31, 0
	s_add_u32 s42, s42, 0x100
	s_addc_u32 s43, s43, 0
	s_cmp_ge_u32 s52, s9
	s_mov_b32 s34, s52
	s_cbranch_scc0 .LBB0_506
	s_and_b64 vcc, exec, s[12:13]
	s_cbranch_vccz .LBB0_509

; #define PG8_STAGE(bufoff, gbase, voff) do { _Pragma("unroll") for (int _i = 0; _i < 2; ++_i) \
;         __builtin_amdgcn_global_load_lds((const unsigned*)((const char*)(gbase) + (voff)[_i]), (LAS unsigned*)(lds + (bufoff) + ldsw + _i * 8192), 16, 0, 0); } while (0)
; #define PG8_LDA(dst, b, h) do { _Pragma("unroll") for (int m = 0; m < 4; ++m) _Pragma("unroll") for (int k = 0; k < 2; ++k) dst[m][k] = *(const LAS bf16x8*)(lds + PG8_SA(b, h) + aoff + m * 2048 + k * KOFF); } while (0)
; #define PG8_LDB(dst, b, h) do { _Pragma("unroll") for (int n = 0; n < 2; ++n) _Pragma("unroll") for (int k = 0; k < 2; ++k) dst[n][k] = *(const LAS bf16x8*)(lds + PG8_SB(b, h) + boff + n * 2048 + k * KOFF); } while (0)
; #define PG8_WAIT_V(n) asm volatile("s_waitcnt vmcnt(" #n ")" ::: "memory")
; #define PG8_WAIT_L(n) asm volatile("s_waitcnt lgkmcnt(" #n ")" ::: "memory")
; #define PG8_BAR __builtin_amdgcn_s_barrier()
; #define PG8_SCHED __builtin_amdgcn_sched_barrier(0)
; template <class Epi, bool ALIGN_EPI = true, bool FP8 = false>
; __device__ __forceinline__ void gemm_phase(LAS unsigned char* lds, const Gemm g, const StaticOrder& S, const Epi& E, const int wid) {
;     ...
;             const char* a1 = cA + (size_t)(t + 1) * kstep;
;             const char* a2 = last ? nA : cA + (size_t)(t + 2) * kstep; const char* b2 = last ? nB : cB + (size_t)(t + 2) * kstep;
;             const char* a3 = a2 + kstep; const char* b3 = b2 + kstep;
;             PG8_LDB(B0, 0, 0); PG8_LDB(B1, 0, 1); PG8_SCHED; PG8_LDA(At, 0, 0); PG8_STAGE(PG8_SA(1, 1), a1 + hstep, voffA);
;             PG8_WAIT_V(8); PG8_WAIT_L(0); PG8_BAR; PG8_MMA(0, 0, At, B0); PG8_MMA(0, 1, At, B1); PG8_BAR; PG8_SCHED;
;             PG8_LDA(At, 0, 1); PG8_STAGE(PG8_SB(0, 0), b2, voffB); PG8_STAGE(PG8_SB(0, 1), b2 + hstep, voffB); PG8_STAGE(PG8_SA(0, 0), a2, voffA);
;             PG8_WAIT_V(8); PG8_WAIT_L(0); PG8_BAR; PG8_MMA(1, 0, At, B0); PG8_MMA(1, 1, At, B1); PG8_BAR; PG8_SCHED;
;             PG8_LDB(B0, 1, 0); PG8_LDB(B1, 1, 1); PG8_SCHED; PG8_LDA(At, 1, 0); PG8_STAGE(PG8_SA(0, 1), a2 + hstep, voffA);
;             PG8_WAIT_V(8); PG8_WAIT_L(0); PG8_BAR; PG8_MMA(0, 0, At, B0); PG8_MMA(0, 1, At, B1); PG8_BAR; PG8_SCHED;
.LBB0_572:
	ds_read_b128 v[152:155], v190
	ds_read_b128 v[156:159], v190 offset:1024
	ds_read_b128 v[144:147], v190 offset:2048
	ds_read_b128 v[148:151], v190 offset:3072
	ds_read_b128 v[136:139], v191
	ds_read_b128 v[140:143], v191 offset:1024
	ds_read_b128 v[128:131], v191 offset:2048
	ds_read_b128 v[132:135], v191 offset:3072
	s_add_i32 s3, s34, 2
	s_add_u32 s35, s30, 0xfffc0080
	s_addc_u32 s36, s31, -1
	s_cmp_eq_u32 s86, s34
	s_cselect_b32 s34, s85, s87
	s_cselect_b32 s37, s21, s36
	s_cselect_b32 s36, s23, s35
	s_cselect_b32 s35, s84, s88
	v_lshl_add_u64 v[220:221], s[30:31], 0, v[170:171]
	s_add_i32 m0, s27, 0xc000
	ds_read_b128 v[178:181], v192
	ds_read_b128 v[182:185], v192 offset:1024
	ds_read_b128 v[196:199], v192 offset:2048
	ds_read_b128 v[200:203], v192 offset:3072
	ds_read_b128 v[204:207], v192 offset:4096
	ds_read_b128 v[208:211], v192 offset:5120
	ds_read_b128 v[212:215], v192 offset:6144
	ds_read_b128 v[216:219], v192 offset:7168
	global_load_lds_dwordx4 v[220:221], off
	v_lshl_add_u64 v[220:221], s[30:31], 0, v[172:173]
	s_add_i32 m0, s27, 0xe000
	s_nop 0
	global_load_lds_dwordx4 v[220:221], off
	s_waitcnt vmcnt(8) lgkmcnt(0)
	s_barrier
	v_mfma_f32_16x16x128_f8f6f4 v[120:123], v[152:159], v[178:185], v[120:123]
	v_mfma_f32_16x16x128_f8f6f4 v[124:127], v[144:151], v[178:185], v[124:127]
	v_mfma_f32_16x16x128_f8f6f4 v[112:115], v[152:159], v[196:203], v[112:115]
	v_mfma_f32_16x16x128_f8f6f4 v[116:119], v[144:151], v[196:203], v[116:119]
	v_mfma_f32_16x16x128_f8f6f4 v[104:107], v[152:159], v[204:211], v[104:107]
	v_mfma_f32_16x16x128_f8f6f4 v[108:111], v[144:151], v[204:211], v[108:111]
	v_mfma_f32_16x16x128_f8f6f4 v[88:91], v[152:159], v[212:219], v[88:91]
	v_mfma_f32_16x16x128_f8f6f4 v[92:95], v[144:151], v[212:219], v[92:95]
	v_mfma_f32_16x16x128_f8f6f4 v[96:99], v[136:143], v[178:185], v[96:99]
	v_mfma_f32_16x16x128_f8f6f4 v[100:103], v[128:135], v[178:185], v[100:103]
	v_mfma_f32_16x16x128_f8f6f4 v[80:83], v[136:143], v[196:203], v[80:83]
	v_mfma_f32_16x16x128_f8f6f4 v[84:87], v[128:135], v[196:203], v[84:87]
	v_mfma_f32_16x16x128_f8f6f4 v[72:75], v[136:143], v[204:211], v[72:75]
	v_mfma_f32_16x16x128_f8f6f4 v[76:79], v[128:135], v[204:211], v[76:79]
	v_mfma_f32_16x16x128_f8f6f4 v[64:67], v[136:143], v[212:219], v[64:67]
	v_mfma_f32_16x16x128_f8f6f4 v[68:71], v[128:135], v[212:219], v[68:71]
	s_barrier
	s_add_i32 s42, s75, s48
	v_lshl_add_u64 v[178:179], s[34:35], 0, v[164:165]
	s_mov_b32 m0, s42
	ds_read_b128 v[196:199], v192 offset:16384
	ds_read_b128 v[200:203], v192 offset:17408
	ds_read_b128 v[204:207], v192 offset:18432
	ds_read_b128 v[208:211], v192 offset:19456
	ds_read_b128 v[212:215], v192 offset:20480
	ds_read_b128 v[216:219], v192 offset:21504
	ds_read_b128 v[220:223], v192 offset:22528
	ds_read_b128 v[224:227], v192 offset:23552
	global_load_lds_dwordx4 v[178:179], off
	s_add_i32 m0, s42, 0x2000
	s_add_u32 s42, s34, 0x40000
	v_lshl_add_u64 v[180:181], s[34:35], 0, v[160:161]
	s_addc_u32 s43, s35, 0
	s_add_i32 s52, s76, s48
	global_load_lds_dwordx4 v[180:181], off
	v_lshl_add_u64 v[182:183], s[42:43], 0, v[164:165]
	s_mov_b32 m0, s52
	v_lshl_add_u64 v[184:185], s[36:37], 0, v[162:163]
	global_load_lds_dwordx4 v[182:183], off
	v_lshl_add_u64 v[182:183], s[42:43], 0, v[160:161]
	s_add_i32 m0, s52, 0x2000
	s_nop 0
	global_load_lds_dwordx4 v[182:183], off
	v_lshl_add_u64 v[182:183], s[36:37], 0, v[166:167]
	s_mov_b32 m0, s27
	s_nop 0
	global_load_lds_dwordx4 v[182:183], off
	s_mov_b32 m0, s55
	s_nop 0
	global_load_lds_dwordx4 v[184:185], off
	s_waitcnt vmcnt(8) lgkmcnt(0)
	s_barrier
	v_mfma_f32_16x16x128_f8f6f4 v[56:59], v[152:159], v[196:203], v[56:59]
	v_mfma_f32_16x16x128_f8f6f4 v[60:63], v[144:151], v[196:203], v[60:63]
	v_mfma_f32_16x16x128_f8f6f4 v[48:51], v[152:159], v[204:211], v[48:51]
	v_mfma_f32_16x16x128_f8f6f4 v[52:55], v[144:151], v[204:211], v[52:55]
	v_mfma_f32_16x16x128_f8f6f4 v[40:43], v[152:159], v[212:219], v[40:43]
	v_mfma_f32_16x16x128_f8f6f4 v[44:47], v[144:151], v[212:219], v[44:47]
	v_mfma_f32_16x16x128_f8f6f4 v[228:231], v[152:159], v[220:227], v[24:27]
	v_mfma_f32_16x16x128_f8f6f4 v[232:235], v[144:151], v[220:227], v[28:31]
	v_mfma_f32_16x16x128_f8f6f4 v[236:239], v[136:143], v[196:203], v[32:35]
	v_mfma_f32_16x16x128_f8f6f4 v[240:243], v[128:135], v[196:203], v[36:39]
	v_mfma_f32_16x16x128_f8f6f4 v[244:247], v[136:143], v[204:211], v[16:19]
	v_mfma_f32_16x16x128_f8f6f4 v[204:207], v[128:135], v[204:211], v[20:23]
	v_mfma_f32_16x16x128_f8f6f4 v[208:211], v[136:143], v[212:219], v[8:11]
	v_mfma_f32_16x16x128_f8f6f4 v[212:215], v[128:135], v[212:219], v[12:15]
	v_mfma_f32_16x16x128_f8f6f4 v[216:219], v[136:143], v[220:227], v[0:3]
	v_mfma_f32_16x16x128_f8f6f4 v[220:223], v[128:135], v[220:227], v[4:7]
	s_barrier
	s_add_i32 s42, 0, 0x18000
	s_add_i32 s43, 0, 0x1c000
	s_nop 0
	v_add_u32_e32 v12, s42, v187
	v_add_u32_e32 v16, s43, v187
	ds_read_b128 v[0:3], v12
	ds_read_b128 v[4:7], v12 offset:1024
	ds_read_b128 v[8:11], v12 offset:2048
	ds_read_b128 v[12:15], v12 offset:3072
	ds_read_b128 v[128:131], v16
	ds_read_b128 v[132:135], v16 offset:1024
	ds_read_b128 v[136:139], v16 offset:2048
	ds_read_b128 v[140:143], v16 offset:3072
	s_add_u32 s36, s36, 0x40000
	s_addc_u32 s37, s37, 0
	s_mov_b32 m0, s64
	v_lshl_add_u64 v[152:153], s[36:37], 0, v[166:167]
	ds_read_b128 v[16:19], v192 offset:32768
	ds_read_b128 v[20:23], v192 offset:33792
	ds_read_b128 v[24:27], v192 offset:34816
	ds_read_b128 v[28:31], v192 offset:35840
	ds_read_b128 v[32:35], v192 offset:36864
	ds_read_b128 v[36:39], v192 offset:37888
	ds_read_b128 v[144:147], v192 offset:38912
	ds_read_b128 v[148:151], v192 offset:39936
	global_load_lds_dwordx4 v[152:153], off
	v_lshl_add_u64 v[152:153], s[36:37], 0, v[162:163]
	s_mov_b32 m0, s65
	s_nop 0
	global_load_lds_dwordx4 v[152:153], off
	s_waitcnt vmcnt(8) lgkmcnt(0)
	s_barrier
; #define PG8_STAGE(bufoff, gbase, voff) do { _Pragma("unroll") for (int _i = 0; _i < 2; ++_i) \
;         __builtin_amdgcn_global_load_lds((const unsigned*)((const char*)(gbase) + (voff)[_i]), (LAS unsigned*)(lds + (bufoff) + ldsw + _i * 8192), 16, 0, 0); } while (0)
; #define PG8_LDA(dst, b, h) do { _Pragma("unroll") for (int m = 0; m < 4; ++m) _Pragma("unroll") for (int k = 0; k < 2; ++k) dst[m][k] = *(const LAS bf16x8*)(lds + PG8_SA(b, h) + aoff + m * 2048 + k * KOFF); } while (0)
; #define PG8_WAIT_V(n) asm volatile("s_waitcnt vmcnt(" #n ")" ::: "memory")
; #define PG8_WAIT_L(n) asm volatile("s_waitcnt lgkmcnt(" #n ")" ::: "memory")
; #define PG8_BAR __builtin_amdgcn_s_barrier()
; #define PG8_SCHED __builtin_amdgcn_sched_barrier(0)
; template <class Epi, bool ALIGN_EPI = true, bool FP8 = false>
; __device__ __forceinline__ void gemm_phase(LAS unsigned char* lds, const Gemm g, const StaticOrder& S, const Epi& E, const int wid) {
;     ...
;             PG8_WAIT_V(8); PG8_WAIT_L(0); PG8_BAR; PG8_MMA(0, 0, At, B0); PG8_MMA(0, 1, At, B1); PG8_BAR; PG8_SCHED;
;             PG8_LDA(At, 1, 1); PG8_STAGE(PG8_SB(1, 0), b3, voffB); PG8_STAGE(PG8_SB(1, 1), b3 + hstep, voffB); PG8_STAGE(PG8_SA(1, 0), a3, voffA);
;             PG8_WAIT_V(8); PG8_WAIT_L(0); PG8_BAR; PG8_MMA(1, 0, At, B0); PG8_MMA(1, 1, At, B1); PG8_BAR; PG8_SCHED;
;         }
	v_mfma_f32_16x16x128_f8f6f4 v[120:123], v[0:7], v[16:23], v[120:123]
	v_mfma_f32_16x16x128_f8f6f4 v[124:127], v[8:15], v[16:23], v[124:127]
	v_mfma_f32_16x16x128_f8f6f4 v[112:115], v[0:7], v[24:31], v[112:115]
	v_mfma_f32_16x16x128_f8f6f4 v[116:119], v[8:15], v[24:31], v[116:119]
	v_mfma_f32_16x16x128_f8f6f4 v[104:107], v[0:7], v[32:39], v[104:107]
	v_mfma_f32_16x16x128_f8f6f4 v[108:111], v[8:15], v[32:39], v[108:111]
	v_mfma_f32_16x16x128_f8f6f4 v[88:91], v[0:7], v[144:151], v[88:91]
	v_mfma_f32_16x16x128_f8f6f4 v[92:95], v[8:15], v[144:151], v[92:95]
	v_mfma_f32_16x16x128_f8f6f4 v[96:99], v[128:135], v[16:23], v[96:99]
	v_mfma_f32_16x16x128_f8f6f4 v[100:103], v[136:143], v[16:23], v[100:103]
	v_mfma_f32_16x16x128_f8f6f4 v[80:83], v[128:135], v[24:31], v[80:83]
	v_mfma_f32_16x16x128_f8f6f4 v[84:87], v[136:143], v[24:31], v[84:87]
	v_mfma_f32_16x16x128_f8f6f4 v[72:75], v[128:135], v[32:39], v[72:75]
	v_mfma_f32_16x16x128_f8f6f4 v[76:79], v[136:143], v[32:39], v[76:79]
	v_mfma_f32_16x16x128_f8f6f4 v[64:67], v[128:135], v[144:151], v[64:67]
	v_mfma_f32_16x16x128_f8f6f4 v[68:71], v[136:143], v[144:151], v[68:71]
	s_barrier
	s_add_i32 s36, s42, s48
	v_lshl_add_u64 v[24:25], v[178:179], 0, s[8:9]
	s_mov_b32 m0, s36
	ds_read_b128 v[16:19], v192 offset:49152
	ds_read_b128 v[20:23], v192 offset:50176
	ds_read_b128 v[144:147], v192 offset:51200
	ds_read_b128 v[148:151], v192 offset:52224
	ds_read_b128 v[152:155], v192 offset:53248
	ds_read_b128 v[156:159], v192 offset:54272
	ds_read_b128 v[196:199], v192 offset:55296
	ds_read_b128 v[200:203], v192 offset:56320
	global_load_lds_dwordx4 v[24:25], off
	s_add_i32 m0, s36, 0x2000
	s_add_u32 s34, s34, 0x40080
	v_lshl_add_u64 v[24:25], v[180:181], 0, s[8:9]
	s_addc_u32 s35, s35, 0
	s_add_i32 s36, s43, s48
	global_load_lds_dwordx4 v[24:25], off
	v_lshl_add_u64 v[24:25], s[34:35], 0, v[164:165]
	s_mov_b32 m0, s36
	s_nop 0
	global_load_lds_dwordx4 v[24:25], off
	v_lshl_add_u64 v[24:25], s[34:35], 0, v[160:161]
	s_add_i32 m0, s36, 0x2000
	s_nop 0
	global_load_lds_dwordx4 v[24:25], off
	v_lshl_add_u64 v[24:25], v[182:183], 0, s[8:9]
	s_mov_b32 m0, s70
	s_nop 0
	global_load_lds_dwordx4 v[24:25], off
	v_lshl_add_u64 v[24:25], v[184:185], 0, s[8:9]
	s_mov_b32 m0, s71
	s_nop 0
	global_load_lds_dwordx4 v[24:25], off
	s_waitcnt vmcnt(8) lgkmcnt(0)
	s_barrier
	v_mfma_f32_16x16x128_f8f6f4 v[56:59], v[0:7], v[16:23], v[56:59]
	v_mfma_f32_16x16x128_f8f6f4 v[60:63], v[8:15], v[16:23], v[60:63]
	v_mfma_f32_16x16x128_f8f6f4 v[48:51], v[0:7], v[144:151], v[48:51]
	v_mfma_f32_16x16x128_f8f6f4 v[52:55], v[8:15], v[144:151], v[52:55]
	v_mfma_f32_16x16x128_f8f6f4 v[40:43], v[0:7], v[152:159], v[40:43]
	v_mfma_f32_16x16x128_f8f6f4 v[44:47], v[8:15], v[152:159], v[44:47]
	v_mfma_f32_16x16x128_f8f6f4 v[24:27], v[0:7], v[196:203], v[228:231]
	v_mfma_f32_16x16x128_f8f6f4 v[28:31], v[8:15], v[196:203], v[232:235]
	v_mfma_f32_16x16x128_f8f6f4 v[32:35], v[128:135], v[16:23], v[236:239]
	v_mfma_f32_16x16x128_f8f6f4 v[36:39], v[136:143], v[16:23], v[240:243]
	v_mfma_f32_16x16x128_f8f6f4 v[16:19], v[128:135], v[144:151], v[244:247]
	v_mfma_f32_16x16x128_f8f6f4 v[20:23], v[136:143], v[144:151], v[204:207]
	v_mfma_f32_16x16x128_f8f6f4 v[8:11], v[128:135], v[152:159], v[208:211]
	v_mfma_f32_16x16x128_f8f6f4 v[12:15], v[136:143], v[152:159], v[212:215]
	v_mfma_f32_16x16x128_f8f6f4 v[0:3], v[128:135], v[196:203], v[216:219]
	v_mfma_f32_16x16x128_f8f6f4 v[4:7], v[136:143], v[196:203], v[220:223]
	s_barrier
	s_add_u32 s30, s30, 0x100
	s_addc_u32 s31, s31, 0
	s_add_u32 s87, s87, 0x100
	s_addc_u32 s88, s88, 0
	s_cmp_ge_u32 s3, s83
	s_mov_b32 s34, s3
	s_cbranch_scc0 .LBB0_572
; __device__ __forceinline__ unsigned cvt_pk_bf16(float lo, float hi) { unsigned r; asm volatile("s_nop 1\n\tv_cvt_pk_bf16_f32 %0, %1, %2" : "=v"(r) : "v"(lo), "v"(hi)); return r; }
; __device__ __forceinline__ unsigned cvt_pk4_fp8(float a, float b, float c, float d) { int w = __builtin_amdgcn_cvt_pk_fp8_f32(fp8_clamp(a), fp8_clamp(b), 0, false); w = __builtin_amdgcn_cvt_pk_fp8_f32(fp8_clamp(c), fp8_clamp(d), w, true); return (unsigned)w; }
; __device__ __forceinline__ float sigmoid_f(float v) { return __builtin_amdgcn_rcpf(1.0f + __builtin_amdgcn_exp2f(-1.4426950408889634f * v)); }
;     __device__ __forceinline__ void operator()(const Acc& acc, const Unit& u, int wr, int wc, int fr, int fq) const {
;     ...
;                         const f32x4 v0 = acc[ai][bj][m][0] * QS, v1 = acc[ai][bj][m][1] * QS;
;                         u32x4 w; w.x = cvt_pk_bf16(v0[0], v0[1]); w.y = cvt_pk_bf16(v0[2], v0[3]); w.z = cvt_pk_bf16(v1[0], v1[1]); w.w = cvt_pk_bf16(v1[2], v1[3]);
;     ...
;                         const f32x4 v0 = acc[ai][bj][m][0] * QS, v1 = acc[ai][bj][m][1] * QS;
;                         u32x2 w; w.x = cvt_pk4_fp8(sigmoid_f(v0[0]) * G_SCALE, sigmoid_f(v0[1]) * G_SCALE, sigmoid_f(v0[2]) * G_SCALE, sigmoid_f(v0[3]) * G_SCALE);
	v_pk_mul_f32 v[122:123], v[122:123], s[14:15] op_sel_hi:[1,0]
	v_pk_mul_f32 v[128:129], v[120:121], s[14:15] op_sel_hi:[1,0]
	v_pk_mul_f32 v[120:121], v[126:127], s[14:15] op_sel_hi:[1,0]
	v_pk_mul_f32 v[124:125], v[124:125], s[14:15] op_sel_hi:[1,0]
	v_pk_mul_f32 v[132:133], v[98:99], s[14:15] op_sel_hi:[1,0]
	v_pk_mul_f32 v[136:137], v[96:97], s[14:15] op_sel_hi:[1,0]
	v_pk_mul_f32 v[130:131], v[102:103], s[14:15] op_sel_hi:[1,0]
	v_pk_mul_f32 v[134:135], v[100:101], s[14:15] op_sel_hi:[1,0]
	v_pk_mul_f32 v[100:101], v[114:115], s[14:15] op_sel_hi:[1,0]
	v_pk_mul_f32 v[112:113], v[112:113], s[14:15] op_sel_hi:[1,0]
	v_pk_mul_f32 v[96:97], v[118:119], s[14:15] op_sel_hi:[1,0]
	v_pk_mul_f32 v[102:103], v[116:117], s[14:15] op_sel_hi:[1,0]
	v_pk_mul_f32 v[116:117], v[82:83], s[14:15] op_sel_hi:[1,0]
	v_pk_mul_f32 v[126:127], v[80:81], s[14:15] op_sel_hi:[1,0]
	v_pk_mul_f32 v[114:115], v[86:87], s[14:15] op_sel_hi:[1,0]
	v_pk_mul_f32 v[118:119], v[84:85], s[14:15] op_sel_hi:[1,0]
	v_pk_mul_f32 v[82:83], v[106:107], s[14:15] op_sel_hi:[1,0]
	v_pk_mul_f32 v[86:87], v[104:105], s[14:15] op_sel_hi:[1,0]
	v_pk_mul_f32 v[80:81], v[110:111], s[14:15] op_sel_hi:[1,0]
	v_pk_mul_f32 v[84:85], v[108:109], s[14:15] op_sel_hi:[1,0]
	v_pk_mul_f32 v[104:105], v[74:75], s[14:15] op_sel_hi:[1,0]
	v_pk_mul_f32 v[108:109], v[72:73], s[14:15] op_sel_hi:[1,0]
	v_pk_mul_f32 v[98:99], v[78:79], s[14:15] op_sel_hi:[1,0]
	v_pk_mul_f32 v[106:107], v[76:77], s[14:15] op_sel_hi:[1,0]
	v_pk_mul_f32 v[74:75], v[90:91], s[14:15] op_sel_hi:[1,0]
	v_pk_mul_f32 v[78:79], v[88:89], s[14:15] op_sel_hi:[1,0]
	v_pk_mul_f32 v[72:73], v[94:95], s[14:15] op_sel_hi:[1,0]
	v_pk_mul_f32 v[76:77], v[92:93], s[14:15] op_sel_hi:[1,0]
	v_pk_mul_f32 v[66:67], v[66:67], s[14:15] op_sel_hi:[1,0]
	v_pk_mul_f32 v[88:89], v[64:65], s[14:15] op_sel_hi:[1,0]
	v_pk_mul_f32 v[64:65], v[70:71], s[14:15] op_sel_hi:[1,0]
	v_pk_mul_f32 v[68:69], v[68:69], s[14:15] op_sel_hi:[1,0]
	v_pk_mul_f32 v[58:59], v[58:59], s[14:15] op_sel_hi:[1,0]
	v_pk_mul_f32 v[70:71], v[56:57], s[14:15] op_sel_hi:[1,0]
	v_pk_mul_f32 v[56:57], v[62:63], s[14:15] op_sel_hi:[1,0]
	v_pk_mul_f32 v[60:61], v[60:61], s[14:15] op_sel_hi:[1,0]
	v_pk_mul_f32 v[92:93], v[34:35], s[14:15] op_sel_hi:[1,0]
	v_pk_mul_f32 v[110:111], v[32:33], s[14:15] op_sel_hi:[1,0]
	v_pk_mul_f32 v[90:91], v[38:39], s[14:15] op_sel_hi:[1,0]
	v_pk_mul_f32 v[94:95], v[36:37], s[14:15] op_sel_hi:[1,0]
	v_pk_mul_f32 v[36:37], v[50:51], s[14:15] op_sel_hi:[1,0]
	v_pk_mul_f32 v[48:49], v[48:49], s[14:15] op_sel_hi:[1,0]
	v_pk_mul_f32 v[32:33], v[54:55], s[14:15] op_sel_hi:[1,0]
	v_pk_mul_f32 v[38:39], v[52:53], s[14:15] op_sel_hi:[1,0]
	v_pk_mul_f32 v[52:53], v[18:19], s[14:15] op_sel_hi:[1,0]
	v_pk_mul_f32 v[62:63], v[16:17], s[14:15] op_sel_hi:[1,0]
	v_pk_mul_f32 v[50:51], v[22:23], s[14:15] op_sel_hi:[1,0]
	v_pk_mul_f32 v[54:55], v[20:21], s[14:15] op_sel_hi:[1,0]
	v_pk_mul_f32 v[18:19], v[42:43], s[14:15] op_sel_hi:[1,0]
	v_pk_mul_f32 v[22:23], v[40:41], s[14:15] op_sel_hi:[1,0]
	v_pk_mul_f32 v[16:17], v[46:47], s[14:15] op_sel_hi:[1,0]
	v_pk_mul_f32 v[20:21], v[44:45], s[14:15] op_sel_hi:[1,0]
	v_pk_mul_f32 v[40:41], v[10:11], s[14:15] op_sel_hi:[1,0]
	v_pk_mul_f32 v[44:45], v[8:9], s[14:15] op_sel_hi:[1,0]
	v_pk_mul_f32 v[34:35], v[14:15], s[14:15] op_sel_hi:[1,0]
	v_pk_mul_f32 v[42:43], v[12:13], s[14:15] op_sel_hi:[1,0]
	v_pk_mul_f32 v[10:11], v[26:27], s[14:15] op_sel_hi:[1,0]
	v_pk_mul_f32 v[14:15], v[24:25], s[14:15] op_sel_hi:[1,0]
	v_pk_mul_f32 v[8:9], v[30:31], s[14:15] op_sel_hi:[1,0]
	v_pk_mul_f32 v[12:13], v[28:29], s[14:15] op_sel_hi:[1,0]
	v_pk_mul_f32 v[2:3], v[2:3], s[14:15] op_sel_hi:[1,0]
	v_pk_mul_f32 v[24:25], v[0:1], s[14:15] op_sel_hi:[1,0]
	v_pk_mul_f32 v[0:1], v[6:7], s[14:15] op_sel_hi:[1,0]
	v_pk_mul_f32 v[4:5], v[4:5], s[14:15] op_sel_hi:[1,0]
	s_and_b64 vcc, exec, s[12:13]
	s_cbranch_vccz .LBB0_575

; #define PG8_STAGE(bufoff, gbase, voff) do { _Pragma("unroll") for (int _i = 0; _i < 2; ++_i) \
;         __builtin_amdgcn_global_load_lds((const unsigned*)((const char*)(gbase) + (voff)[_i]), (LAS unsigned*)(lds + (bufoff) + ldsw + _i * 8192), 16, 0, 0); } while (0)
; #define PG8_LDA(dst, b, h) do { _Pragma("unroll") for (int m = 0; m < 4; ++m) _Pragma("unroll") for (int k = 0; k < 2; ++k) dst[m][k] = *(const LAS bf16x8*)(lds + PG8_SA(b, h) + aoff + m * 2048 + k * KOFF); } while (0)
; #define PG8_LDB(dst, b, h) do { _Pragma("unroll") for (int n = 0; n < 2; ++n) _Pragma("unroll") for (int k = 0; k < 2; ++k) dst[n][k] = *(const LAS bf16x8*)(lds + PG8_SB(b, h) + boff + n * 2048 + k * KOFF); } while (0)
; #define PG8_WAIT_V(n) asm volatile("s_waitcnt vmcnt(" #n ")" ::: "memory")
; #define PG8_WAIT_L(n) asm volatile("s_waitcnt lgkmcnt(" #n ")" ::: "memory")
; #define PG8_BAR __builtin_amdgcn_s_barrier()
; #define PG8_SCHED __builtin_amdgcn_sched_barrier(0)
; template <class Epi, bool ALIGN_EPI = true, bool FP8 = false>
; __device__ __forceinline__ void gemm_phase(LAS unsigned char* lds, const Gemm g, const StaticOrder& S, const Epi& E, const int wid) {
;     ...
;             const char* a1 = cA + (size_t)(t + 1) * kstep;
;             const char* a2 = last ? nA : cA + (size_t)(t + 2) * kstep; const char* b2 = last ? nB : cB + (size_t)(t + 2) * kstep;
;             const char* a3 = a2 + kstep; const char* b3 = b2 + kstep;
;             PG8_LDB(B0, 0, 0); PG8_LDB(B1, 0, 1); PG8_SCHED; PG8_LDA(At, 0, 0); PG8_STAGE(PG8_SA(1, 1), a1 + hstep, voffA);
;             PG8_WAIT_V(8); PG8_WAIT_L(0); PG8_BAR; PG8_MMA(0, 0, At, B0); PG8_MMA(0, 1, At, B1); PG8_BAR; PG8_SCHED;
;             PG8_LDA(At, 0, 1); PG8_STAGE(PG8_SB(0, 0), b2, voffB); PG8_STAGE(PG8_SB(0, 1), b2 + hstep, voffB); PG8_STAGE(PG8_SA(0, 0), a2, voffA);
;             PG8_WAIT_V(8); PG8_WAIT_L(0); PG8_BAR; PG8_MMA(1, 0, At, B0); PG8_MMA(1, 1, At, B1); PG8_BAR; PG8_SCHED;
.LBB0_2058:
	v_add_u32_e32 v128, s83, v192
	v_add_u32_e32 v132, s84, v192
	ds_read_b128 v[152:155], v128
	ds_read_b128 v[156:159], v128 offset:1024
	ds_read_b128 v[144:147], v128 offset:2048
	ds_read_b128 v[148:151], v128 offset:3072
	ds_read_b128 v[136:139], v132
	ds_read_b128 v[140:143], v132 offset:1024
	ds_read_b128 v[128:131], v132 offset:2048
	ds_read_b128 v[132:135], v132 offset:3072
	s_add_i32 s3, s42, 2
	s_add_u32 s43, s64, 0xfffe0080
	s_addc_u32 s52, s65, -1
	s_cmp_eq_u32 s35, s42
	s_cselect_b32 s69, s11, s52
	s_cselect_b32 s68, s16, s43
	s_cselect_b32 s67, s29, s90
	s_cselect_b32 s66, s31, s89
	v_lshl_add_u64 v[188:189], s[64:65], 0, v[174:175]
	s_add_i32 m0, s72, 0xc000
	ds_read_b128 v[180:183], v193
	ds_read_b128 v[184:187], v193 offset:1024
	ds_read_b128 v[196:199], v193 offset:2048
	ds_read_b128 v[200:203], v193 offset:3072
	ds_read_b128 v[204:207], v193 offset:4096
	ds_read_b128 v[208:211], v193 offset:5120
	ds_read_b128 v[212:215], v193 offset:6144
	ds_read_b128 v[216:219], v193 offset:7168
	global_load_lds_dwordx4 v[188:189], off
	v_lshl_add_u64 v[188:189], s[64:65], 0, v[176:177]
	s_add_i32 m0, s72, 0xe000
	s_nop 0
	global_load_lds_dwordx4 v[188:189], off
	s_waitcnt vmcnt(8) lgkmcnt(0)
	s_barrier
	v_mfma_f32_16x16x128_f8f6f4 v[120:123], v[152:159], v[180:187], v[120:123]
	v_mfma_f32_16x16x128_f8f6f4 v[124:127], v[144:151], v[180:187], v[124:127]
	v_mfma_f32_16x16x128_f8f6f4 v[112:115], v[152:159], v[196:203], v[112:115]
	v_mfma_f32_16x16x128_f8f6f4 v[116:119], v[144:151], v[196:203], v[116:119]
	v_mfma_f32_16x16x128_f8f6f4 v[104:107], v[152:159], v[204:211], v[104:107]
	v_mfma_f32_16x16x128_f8f6f4 v[108:111], v[144:151], v[204:211], v[108:111]
	v_mfma_f32_16x16x128_f8f6f4 v[96:99], v[152:159], v[212:219], v[96:99]
	v_mfma_f32_16x16x128_f8f6f4 v[100:103], v[144:151], v[212:219], v[100:103]
	v_mfma_f32_16x16x128_f8f6f4 v[88:91], v[136:143], v[180:187], v[88:91]
	v_mfma_f32_16x16x128_f8f6f4 v[92:95], v[128:135], v[180:187], v[92:95]
	v_mfma_f32_16x16x128_f8f6f4 v[80:83], v[136:143], v[196:203], v[80:83]
	v_mfma_f32_16x16x128_f8f6f4 v[84:87], v[128:135], v[196:203], v[84:87]
	v_mfma_f32_16x16x128_f8f6f4 v[72:75], v[136:143], v[204:211], v[72:75]
	v_mfma_f32_16x16x128_f8f6f4 v[76:79], v[128:135], v[204:211], v[76:79]
	v_mfma_f32_16x16x128_f8f6f4 v[64:67], v[136:143], v[212:219], v[64:67]
	v_mfma_f32_16x16x128_f8f6f4 v[68:71], v[128:135], v[212:219], v[68:71]
	s_barrier
	s_add_i32 s42, s83, s71
	v_lshl_add_u64 v[180:181], s[66:67], 0, v[162:163]
	s_mov_b32 m0, s42
	ds_read_b128 v[196:199], v193 offset:16384
	ds_read_b128 v[200:203], v193 offset:17408
	ds_read_b128 v[204:207], v193 offset:18432
	ds_read_b128 v[208:211], v193 offset:19456
	ds_read_b128 v[212:215], v193 offset:20480
	ds_read_b128 v[216:219], v193 offset:21504
	ds_read_b128 v[220:223], v193 offset:22528
	ds_read_b128 v[224:227], v193 offset:23552
	global_load_lds_dwordx4 v[180:181], off
	s_add_i32 m0, s42, 0x2000
	s_add_u32 s42, s66, 0x20000
	v_lshl_add_u64 v[182:183], s[66:67], 0, v[166:167]
	s_addc_u32 s43, s67, 0
	s_add_i32 s52, s84, s71
	global_load_lds_dwordx4 v[182:183], off
	v_lshl_add_u64 v[184:185], s[42:43], 0, v[162:163]
	s_mov_b32 m0, s52
	v_lshl_add_u64 v[186:187], s[68:69], 0, v[164:165]
	global_load_lds_dwordx4 v[184:185], off
	v_lshl_add_u64 v[184:185], s[42:43], 0, v[166:167]
	s_add_i32 m0, s52, 0x2000
	s_nop 0
	global_load_lds_dwordx4 v[184:185], off
	v_lshl_add_u64 v[184:185], s[68:69], 0, v[160:161]
	s_mov_b32 m0, s72
	s_nop 0
	global_load_lds_dwordx4 v[184:185], off
	s_mov_b32 m0, s73
	s_nop 0
	global_load_lds_dwordx4 v[186:187], off
	s_waitcnt vmcnt(8) lgkmcnt(0)
	s_barrier
	v_mfma_f32_16x16x128_f8f6f4 v[56:59], v[152:159], v[196:203], v[56:59]
	v_mfma_f32_16x16x128_f8f6f4 v[60:63], v[144:151], v[196:203], v[60:63]
	v_mfma_f32_16x16x128_f8f6f4 v[48:51], v[152:159], v[204:211], v[48:51]
	v_mfma_f32_16x16x128_f8f6f4 v[52:55], v[144:151], v[204:211], v[52:55]
	v_mfma_f32_16x16x128_f8f6f4 v[40:43], v[152:159], v[212:219], v[40:43]
	v_mfma_f32_16x16x128_f8f6f4 v[44:47], v[144:151], v[212:219], v[44:47]
	v_mfma_f32_16x16x128_f8f6f4 v[188:191], v[152:159], v[220:227], v[32:35]
	v_mfma_f32_16x16x128_f8f6f4 v[228:231], v[144:151], v[220:227], v[36:39]
	v_mfma_f32_16x16x128_f8f6f4 v[232:235], v[136:143], v[196:203], v[24:27]
	v_mfma_f32_16x16x128_f8f6f4 v[236:239], v[128:135], v[196:203], v[28:31]
	v_mfma_f32_16x16x128_f8f6f4 v[240:243], v[136:143], v[204:211], v[16:19]
	v_mfma_f32_16x16x128_f8f6f4 v[204:207], v[128:135], v[204:211], v[20:23]
	v_mfma_f32_16x16x128_f8f6f4 v[208:211], v[136:143], v[212:219], v[8:11]
	v_mfma_f32_16x16x128_f8f6f4 v[212:215], v[128:135], v[212:219], v[12:15]
	v_mfma_f32_16x16x128_f8f6f4 v[216:219], v[136:143], v[220:227], v[0:3]
	v_mfma_f32_16x16x128_f8f6f4 v[220:223], v[128:135], v[220:227], v[4:7]
	s_barrier
; #define PG8_STAGE(bufoff, gbase, voff) do { _Pragma("unroll") for (int _i = 0; _i < 2; ++_i) \
;         __builtin_amdgcn_global_load_lds((const unsigned*)((const char*)(gbase) + (voff)[_i]), (LAS unsigned*)(lds + (bufoff) + ldsw + _i * 8192), 16, 0, 0); } while (0)
; #define PG8_LDA(dst, b, h) do { _Pragma("unroll") for (int m = 0; m < 4; ++m) _Pragma("unroll") for (int k = 0; k < 2; ++k) dst[m][k] = *(const LAS bf16x8*)(lds + PG8_SA(b, h) + aoff + m * 2048 + k * KOFF); } while (0)
; #define PG8_LDB(dst, b, h) do { _Pragma("unroll") for (int n = 0; n < 2; ++n) _Pragma("unroll") for (int k = 0; k < 2; ++k) dst[n][k] = *(const LAS bf16x8*)(lds + PG8_SB(b, h) + boff + n * 2048 + k * KOFF); } while (0)
; #define PG8_WAIT_V(n) asm volatile("s_waitcnt vmcnt(" #n ")" ::: "memory")
; #define PG8_WAIT_L(n) asm volatile("s_waitcnt lgkmcnt(" #n ")" ::: "memory")
; #define PG8_BAR __builtin_amdgcn_s_barrier()
; #define PG8_SCHED __builtin_amdgcn_sched_barrier(0)
; template <class Epi, bool ALIGN_EPI = true, bool FP8 = false>
; __device__ __forceinline__ void gemm_phase(LAS unsigned char* lds, const Gemm g, const StaticOrder& S, const Epi& E, const int wid) {
;     ...
;             PG8_LDB(B0, 1, 0); PG8_LDB(B1, 1, 1); PG8_SCHED; PG8_LDA(At, 1, 0); PG8_STAGE(PG8_SA(0, 1), a2 + hstep, voffA);
;             PG8_WAIT_V(8); PG8_WAIT_L(0); PG8_BAR; PG8_MMA(0, 0, At, B0); PG8_MMA(0, 1, At, B1); PG8_BAR; PG8_SCHED;
;             PG8_LDA(At, 1, 1); PG8_STAGE(PG8_SB(1, 0), b3, voffB); PG8_STAGE(PG8_SB(1, 1), b3 + hstep, voffB); PG8_STAGE(PG8_SA(1, 0), a3, voffA);
;             PG8_WAIT_V(8); PG8_WAIT_L(0); PG8_BAR; PG8_MMA(1, 0, At, B0); PG8_MMA(1, 1, At, B1); PG8_BAR; PG8_SCHED;
;         }
	s_add_i32 s52, 0, 0x18000
	s_add_i32 s54, 0, 0x1c000
	s_nop 0
	v_add_u32_e32 v12, s52, v192
	v_add_u32_e32 v16, s54, v192
	ds_read_b128 v[0:3], v12
	ds_read_b128 v[4:7], v12 offset:1024
	ds_read_b128 v[8:11], v12 offset:2048
	ds_read_b128 v[12:15], v12 offset:3072
	ds_read_b128 v[128:131], v16
	ds_read_b128 v[132:135], v16 offset:1024
	ds_read_b128 v[136:139], v16 offset:2048
	ds_read_b128 v[140:143], v16 offset:3072
	s_add_u32 s42, s68, 0x20000
	s_addc_u32 s43, s69, 0
	s_mov_b32 m0, s74
	v_lshl_add_u64 v[152:153], s[42:43], 0, v[160:161]
	ds_read_b128 v[16:19], v193 offset:32768
	ds_read_b128 v[20:23], v193 offset:33792
	ds_read_b128 v[24:27], v193 offset:34816
	ds_read_b128 v[28:31], v193 offset:35840
	ds_read_b128 v[32:35], v193 offset:36864
	ds_read_b128 v[36:39], v193 offset:37888
	ds_read_b128 v[144:147], v193 offset:38912
	ds_read_b128 v[148:151], v193 offset:39936
	global_load_lds_dwordx4 v[152:153], off
	v_lshl_add_u64 v[152:153], s[42:43], 0, v[164:165]
	s_mov_b32 m0, s75
	s_nop 0
	global_load_lds_dwordx4 v[152:153], off
	s_waitcnt vmcnt(8) lgkmcnt(0)
	s_barrier
	v_mfma_f32_16x16x128_f8f6f4 v[120:123], v[0:7], v[16:23], v[120:123]
	v_mfma_f32_16x16x128_f8f6f4 v[124:127], v[8:15], v[16:23], v[124:127]
	v_mfma_f32_16x16x128_f8f6f4 v[112:115], v[0:7], v[24:31], v[112:115]
	v_mfma_f32_16x16x128_f8f6f4 v[116:119], v[8:15], v[24:31], v[116:119]
	v_mfma_f32_16x16x128_f8f6f4 v[104:107], v[0:7], v[32:39], v[104:107]
	v_mfma_f32_16x16x128_f8f6f4 v[108:111], v[8:15], v[32:39], v[108:111]
	v_mfma_f32_16x16x128_f8f6f4 v[96:99], v[0:7], v[144:151], v[96:99]
	v_mfma_f32_16x16x128_f8f6f4 v[100:103], v[8:15], v[144:151], v[100:103]
	v_mfma_f32_16x16x128_f8f6f4 v[88:91], v[128:135], v[16:23], v[88:91]
	v_mfma_f32_16x16x128_f8f6f4 v[92:95], v[136:143], v[16:23], v[92:95]
	v_mfma_f32_16x16x128_f8f6f4 v[80:83], v[128:135], v[24:31], v[80:83]
	v_mfma_f32_16x16x128_f8f6f4 v[84:87], v[136:143], v[24:31], v[84:87]
	v_mfma_f32_16x16x128_f8f6f4 v[72:75], v[128:135], v[32:39], v[72:75]
	v_mfma_f32_16x16x128_f8f6f4 v[76:79], v[136:143], v[32:39], v[76:79]
	v_mfma_f32_16x16x128_f8f6f4 v[64:67], v[128:135], v[144:151], v[64:67]
	v_mfma_f32_16x16x128_f8f6f4 v[68:71], v[136:143], v[144:151], v[68:71]
	s_barrier
	s_add_i32 s42, s52, s71
	v_lshl_add_u64 v[24:25], v[180:181], 0, s[20:21]
	s_mov_b32 m0, s42
	ds_read_b128 v[16:19], v193 offset:49152
	ds_read_b128 v[20:23], v193 offset:50176
	ds_read_b128 v[144:147], v193 offset:51200
	ds_read_b128 v[148:151], v193 offset:52224
	ds_read_b128 v[152:155], v193 offset:53248
	ds_read_b128 v[156:159], v193 offset:54272
	ds_read_b128 v[196:199], v193 offset:55296
	ds_read_b128 v[200:203], v193 offset:56320
	global_load_lds_dwordx4 v[24:25], off
	s_add_i32 m0, s42, 0x2000
	s_add_u32 s42, s66, 0x20080
	v_lshl_add_u64 v[24:25], v[182:183], 0, s[20:21]
	s_addc_u32 s43, s67, 0
	s_add_i32 s52, s54, s71
	global_load_lds_dwordx4 v[24:25], off
	v_lshl_add_u64 v[24:25], s[42:43], 0, v[162:163]
	s_mov_b32 m0, s52
	s_nop 0
	global_load_lds_dwordx4 v[24:25], off
	v_lshl_add_u64 v[24:25], s[42:43], 0, v[166:167]
	s_add_i32 m0, s52, 0x2000
	s_nop 0
	global_load_lds_dwordx4 v[24:25], off
	v_lshl_add_u64 v[24:25], v[184:185], 0, s[20:21]
	s_mov_b32 m0, s80
	s_nop 0
	global_load_lds_dwordx4 v[24:25], off
	v_lshl_add_u64 v[24:25], v[186:187], 0, s[20:21]
	s_mov_b32 m0, s81
	s_nop 0
	global_load_lds_dwordx4 v[24:25], off
	s_waitcnt vmcnt(8) lgkmcnt(0)
	s_barrier
	v_mfma_f32_16x16x128_f8f6f4 v[56:59], v[0:7], v[16:23], v[56:59]
	v_mfma_f32_16x16x128_f8f6f4 v[60:63], v[8:15], v[16:23], v[60:63]
	v_mfma_f32_16x16x128_f8f6f4 v[48:51], v[0:7], v[144:151], v[48:51]
	v_mfma_f32_16x16x128_f8f6f4 v[52:55], v[8:15], v[144:151], v[52:55]
	v_mfma_f32_16x16x128_f8f6f4 v[40:43], v[0:7], v[152:159], v[40:43]
	v_mfma_f32_16x16x128_f8f6f4 v[44:47], v[8:15], v[152:159], v[44:47]
	v_mfma_f32_16x16x128_f8f6f4 v[32:35], v[0:7], v[196:203], v[188:191]
	v_mfma_f32_16x16x128_f8f6f4 v[36:39], v[8:15], v[196:203], v[228:231]
	v_mfma_f32_16x16x128_f8f6f4 v[24:27], v[128:135], v[16:23], v[232:235]
	v_mfma_f32_16x16x128_f8f6f4 v[28:31], v[136:143], v[16:23], v[236:239]
	v_mfma_f32_16x16x128_f8f6f4 v[16:19], v[128:135], v[144:151], v[240:243]
	v_mfma_f32_16x16x128_f8f6f4 v[20:23], v[136:143], v[144:151], v[204:207]
	v_mfma_f32_16x16x128_f8f6f4 v[8:11], v[128:135], v[152:159], v[208:211]
	v_mfma_f32_16x16x128_f8f6f4 v[12:15], v[136:143], v[152:159], v[212:215]
	v_mfma_f32_16x16x128_f8f6f4 v[0:3], v[128:135], v[196:203], v[216:219]
	v_mfma_f32_16x16x128_f8f6f4 v[4:7], v[136:143], v[196:203], v[220:223]
	s_barrier
	s_add_u32 s64, s64, 0x100
	s_addc_u32 s65, s65, 0
	s_add_u32 s89, s89, 0x100
	s_addc_u32 s90, s90, 0
	s_cmp_ge_u32 s3, s9
	s_mov_b32 s42, s3
	s_cbranch_scc0 .LBB0_2058
	s_and_b64 vcc, exec, s[22:23]
	s_cbranch_vccz .LBB0_2061
	s_barrier

; #define PG8_STAGE(bufoff, gbase, voff) do { _Pragma("unroll") for (int _i = 0; _i < 2; ++_i) \
;         __builtin_amdgcn_global_load_lds((const unsigned*)((const char*)(gbase) + (voff)[_i]), (LAS unsigned*)(lds + (bufoff) + ldsw + _i * 8192), 16, 0, 0); } while (0)
; #define PG8_LDA(dst, b, h) do { _Pragma("unroll") for (int m = 0; m < 4; ++m) _Pragma("unroll") for (int k = 0; k < 2; ++k) dst[m][k] = *(const LAS bf16x8*)(lds + PG8_SA(b, h) + aoff + m * 2048 + k * KOFF); } while (0)
; #define PG8_LDB(dst, b, h) do { _Pragma("unroll") for (int n = 0; n < 2; ++n) _Pragma("unroll") for (int k = 0; k < 2; ++k) dst[n][k] = *(const LAS bf16x8*)(lds + PG8_SB(b, h) + boff + n * 2048 + k * KOFF); } while (0)
; #define PG8_WAIT_V(n) asm volatile("s_waitcnt vmcnt(" #n ")" ::: "memory")
; #define PG8_WAIT_L(n) asm volatile("s_waitcnt lgkmcnt(" #n ")" ::: "memory")
; #define PG8_BAR __builtin_amdgcn_s_barrier()
; #define PG8_SCHED __builtin_amdgcn_sched_barrier(0)
; template <class Epi, bool ALIGN_EPI = true, bool FP8 = false>
; __device__ __forceinline__ void gemm_phase(LAS unsigned char* lds, const Gemm g, const StaticOrder& S, const Epi& E, const int wid) {
;     ...
;             const char* a1 = cA + (size_t)(t + 1) * kstep;
;             const char* a2 = last ? nA : cA + (size_t)(t + 2) * kstep; const char* b2 = last ? nB : cB + (size_t)(t + 2) * kstep;
;             const char* a3 = a2 + kstep; const char* b3 = b2 + kstep;
;             PG8_LDB(B0, 0, 0); PG8_LDB(B1, 0, 1); PG8_SCHED; PG8_LDA(At, 0, 0); PG8_STAGE(PG8_SA(1, 1), a1 + hstep, voffA);
;             PG8_WAIT_V(8); PG8_WAIT_L(0); PG8_BAR; PG8_MMA(0, 0, At, B0); PG8_MMA(0, 1, At, B1); PG8_BAR; PG8_SCHED;
;             PG8_LDA(At, 0, 1); PG8_STAGE(PG8_SB(0, 0), b2, voffB); PG8_STAGE(PG8_SB(0, 1), b2 + hstep, voffB); PG8_STAGE(PG8_SA(0, 0), a2, voffA);
;             PG8_WAIT_V(8); PG8_WAIT_L(0); PG8_BAR; PG8_MMA(1, 0, At, B0); PG8_MMA(1, 1, At, B1); PG8_BAR; PG8_SCHED;
.LBB0_2290:
	ds_read_b128 v[152:155], v218
	ds_read_b128 v[156:159], v218 offset:1024
	ds_read_b128 v[144:147], v218 offset:2048
	ds_read_b128 v[148:151], v218 offset:3072
	ds_read_b128 v[136:139], v219
	ds_read_b128 v[140:143], v219 offset:1024
	ds_read_b128 v[128:131], v219 offset:2048
	ds_read_b128 v[132:135], v219 offset:3072
	s_add_i32 s3, s38, 2
	s_add_u32 s36, s34, 0xfffc0080
	s_addc_u32 s37, s35, -1
	s_cmp_eq_u32 s88, s38
	s_cselect_b32 s38, s31, s36
	s_cselect_b32 s39, s21, s37
	s_cselect_b32 s37, s19, s90
	s_cselect_b32 s36, s87, s89
	v_lshl_add_u64 v[212:213], s[34:35], 0, v[198:199]
	s_add_i32 m0, s27, 0xc000
	ds_read_b128 v[160:163], v220
	ds_read_b128 v[164:167], v220 offset:1024
	ds_read_b128 v[168:171], v220 offset:2048
	ds_read_b128 v[172:175], v220 offset:3072
	ds_read_b128 v[176:179], v220 offset:4096
	ds_read_b128 v[180:183], v220 offset:5120
	ds_read_b128 v[204:207], v220 offset:6144
	ds_read_b128 v[208:211], v220 offset:7168
	global_load_lds_dwordx4 v[212:213], off
	v_lshl_add_u64 v[212:213], s[34:35], 0, v[200:201]
	s_add_i32 m0, s27, 0xe000
	s_nop 0
	global_load_lds_dwordx4 v[212:213], off
	s_waitcnt vmcnt(8) lgkmcnt(0)
	s_barrier
	v_mfma_f32_16x16x128_f8f6f4 v[120:123], v[152:159], v[160:167], v[120:123]
	v_mfma_f32_16x16x128_f8f6f4 v[124:127], v[144:151], v[160:167], v[124:127]
	v_mfma_f32_16x16x128_f8f6f4 v[104:107], v[152:159], v[168:175], v[104:107]
	v_mfma_f32_16x16x128_f8f6f4 v[108:111], v[144:151], v[168:175], v[108:111]
	v_mfma_f32_16x16x128_f8f6f4 v[96:99], v[152:159], v[176:183], v[96:99]
	v_mfma_f32_16x16x128_f8f6f4 v[100:103], v[144:151], v[176:183], v[100:103]
	v_mfma_f32_16x16x128_f8f6f4 v[80:83], v[152:159], v[204:211], v[80:83]
	v_mfma_f32_16x16x128_f8f6f4 v[84:87], v[144:151], v[204:211], v[84:87]
	v_mfma_f32_16x16x128_f8f6f4 v[112:115], v[136:143], v[160:167], v[112:115]
	v_mfma_f32_16x16x128_f8f6f4 v[116:119], v[128:135], v[160:167], v[116:119]
	v_mfma_f32_16x16x128_f8f6f4 v[88:91], v[136:143], v[168:175], v[88:91]
	v_mfma_f32_16x16x128_f8f6f4 v[92:95], v[128:135], v[168:175], v[92:95]
	v_mfma_f32_16x16x128_f8f6f4 v[72:75], v[136:143], v[176:183], v[72:75]
	v_mfma_f32_16x16x128_f8f6f4 v[76:79], v[128:135], v[176:183], v[76:79]
	v_mfma_f32_16x16x128_f8f6f4 v[64:67], v[136:143], v[204:211], v[64:67]
	v_mfma_f32_16x16x128_f8f6f4 v[68:71], v[128:135], v[204:211], v[68:71]
	s_barrier
	s_add_i32 s42, s75, s53
	v_lshl_add_u64 v[160:161], s[36:37], 0, v[188:189]
	s_mov_b32 m0, s42
	ds_read_b128 v[168:171], v220 offset:16384
	ds_read_b128 v[172:175], v220 offset:17408
	ds_read_b128 v[176:179], v220 offset:18432
	ds_read_b128 v[180:183], v220 offset:19456
	ds_read_b128 v[204:207], v220 offset:20480
	ds_read_b128 v[208:211], v220 offset:21504
	ds_read_b128 v[222:225], v220 offset:22528
	ds_read_b128 v[226:229], v220 offset:23552
	global_load_lds_dwordx4 v[160:161], off
	s_add_i32 m0, s42, 0x2000
	s_add_u32 s42, s36, 0x40000
	v_lshl_add_u64 v[162:163], s[36:37], 0, v[184:185]
	s_addc_u32 s43, s37, 0
	s_add_i32 s52, s76, s53
	global_load_lds_dwordx4 v[162:163], off
	v_lshl_add_u64 v[164:165], s[42:43], 0, v[188:189]
	s_mov_b32 m0, s52
	v_lshl_add_u64 v[166:167], s[38:39], 0, v[186:187]
	global_load_lds_dwordx4 v[164:165], off
	v_lshl_add_u64 v[164:165], s[42:43], 0, v[184:185]
	s_add_i32 m0, s52, 0x2000
	s_nop 0
	global_load_lds_dwordx4 v[164:165], off
	v_lshl_add_u64 v[164:165], s[38:39], 0, v[190:191]
	s_mov_b32 m0, s27
	s_nop 0
	global_load_lds_dwordx4 v[164:165], off
	s_mov_b32 m0, s55
	s_nop 0
	global_load_lds_dwordx4 v[166:167], off
	s_waitcnt vmcnt(8) lgkmcnt(0)
	s_barrier
	v_mfma_f32_16x16x128_f8f6f4 v[56:59], v[152:159], v[168:175], v[56:59]
	v_mfma_f32_16x16x128_f8f6f4 v[60:63], v[144:151], v[168:175], v[60:63]
	v_mfma_f32_16x16x128_f8f6f4 v[48:51], v[152:159], v[176:183], v[48:51]
	v_mfma_f32_16x16x128_f8f6f4 v[52:55], v[144:151], v[176:183], v[52:55]
	v_mfma_f32_16x16x128_f8f6f4 v[32:35], v[152:159], v[204:211], v[32:35]
	v_mfma_f32_16x16x128_f8f6f4 v[212:215], v[144:151], v[204:211], v[36:39]
	v_mfma_f32_16x16x128_f8f6f4 v[230:233], v[152:159], v[222:229], v[16:19]
	v_mfma_f32_16x16x128_f8f6f4 v[234:237], v[144:151], v[222:229], v[20:23]
	v_mfma_f32_16x16x128_f8f6f4 v[44:47], v[128:135], v[168:175], v[44:47]
	v_mfma_f32_16x16x128_f8f6f4 v[238:241], v[136:143], v[168:175], v[40:43]
	v_mfma_f32_16x16x128_f8f6f4 v[242:245], v[136:143], v[176:183], v[24:27]
	v_mfma_f32_16x16x128_f8f6f4 v[176:179], v[128:135], v[176:183], v[28:31]
	v_mfma_f32_16x16x128_f8f6f4 v[180:183], v[136:143], v[204:211], v[8:11]
	v_mfma_f32_16x16x128_f8f6f4 v[204:207], v[128:135], v[204:211], v[12:15]
	v_mfma_f32_16x16x128_f8f6f4 v[208:211], v[136:143], v[222:229], v[0:3]
	v_mfma_f32_16x16x128_f8f6f4 v[222:225], v[128:135], v[222:229], v[4:7]
	s_barrier
; #define PG8_STAGE(bufoff, gbase, voff) do { _Pragma("unroll") for (int _i = 0; _i < 2; ++_i) \
;         __builtin_amdgcn_global_load_lds((const unsigned*)((const char*)(gbase) + (voff)[_i]), (LAS unsigned*)(lds + (bufoff) + ldsw + _i * 8192), 16, 0, 0); } while (0)
; #define PG8_LDA(dst, b, h) do { _Pragma("unroll") for (int m = 0; m < 4; ++m) _Pragma("unroll") for (int k = 0; k < 2; ++k) dst[m][k] = *(const LAS bf16x8*)(lds + PG8_SA(b, h) + aoff + m * 2048 + k * KOFF); } while (0)
; #define PG8_LDB(dst, b, h) do { _Pragma("unroll") for (int n = 0; n < 2; ++n) _Pragma("unroll") for (int k = 0; k < 2; ++k) dst[n][k] = *(const LAS bf16x8*)(lds + PG8_SB(b, h) + boff + n * 2048 + k * KOFF); } while (0)
; #define PG8_WAIT_V(n) asm volatile("s_waitcnt vmcnt(" #n ")" ::: "memory")
; #define PG8_WAIT_L(n) asm volatile("s_waitcnt lgkmcnt(" #n ")" ::: "memory")
; #define PG8_BAR __builtin_amdgcn_s_barrier()
; #define PG8_SCHED __builtin_amdgcn_sched_barrier(0)
; template <class Epi, bool ALIGN_EPI = true, bool FP8 = false>
; __device__ __forceinline__ void gemm_phase(LAS unsigned char* lds, const Gemm g, const StaticOrder& S, const Epi& E, const int wid) {
;     ...
;             PG8_LDB(B0, 1, 0); PG8_LDB(B1, 1, 1); PG8_SCHED; PG8_LDA(At, 1, 0); PG8_STAGE(PG8_SA(0, 1), a2 + hstep, voffA);
;             PG8_WAIT_V(8); PG8_WAIT_L(0); PG8_BAR; PG8_MMA(0, 0, At, B0); PG8_MMA(0, 1, At, B1); PG8_BAR; PG8_SCHED;
;             PG8_LDA(At, 1, 1); PG8_STAGE(PG8_SB(1, 0), b3, voffB); PG8_STAGE(PG8_SB(1, 1), b3 + hstep, voffB); PG8_STAGE(PG8_SA(1, 0), a3, voffA);
;             PG8_WAIT_V(8); PG8_WAIT_L(0); PG8_BAR; PG8_MMA(1, 0, At, B0); PG8_MMA(1, 1, At, B1); PG8_BAR; PG8_SCHED;
;         }
	s_add_i32 s42, 0, 0x18000
	s_add_i32 s43, 0, 0x1c000
	s_nop 0
	v_add_u32_e32 v12, s42, v217
	v_add_u32_e32 v16, s43, v217
	ds_read_b128 v[0:3], v12
	ds_read_b128 v[4:7], v12 offset:1024
	ds_read_b128 v[8:11], v12 offset:2048
	ds_read_b128 v[12:15], v12 offset:3072
	ds_read_b128 v[128:131], v16
	ds_read_b128 v[132:135], v16 offset:1024
	ds_read_b128 v[136:139], v16 offset:2048
	ds_read_b128 v[140:143], v16 offset:3072
	s_add_u32 s38, s38, 0x40000
	s_addc_u32 s39, s39, 0
	s_mov_b32 m0, s64
	v_lshl_add_u64 v[152:153], s[38:39], 0, v[190:191]
	ds_read_b128 v[16:19], v220 offset:32768
	ds_read_b128 v[20:23], v220 offset:33792
	ds_read_b128 v[24:27], v220 offset:34816
	ds_read_b128 v[28:31], v220 offset:35840
	ds_read_b128 v[36:39], v220 offset:36864
	ds_read_b128 v[40:43], v220 offset:37888
	ds_read_b128 v[144:147], v220 offset:38912
	ds_read_b128 v[148:151], v220 offset:39936
	global_load_lds_dwordx4 v[152:153], off
	v_lshl_add_u64 v[152:153], s[38:39], 0, v[186:187]
	s_mov_b32 m0, s65
	s_nop 0
	global_load_lds_dwordx4 v[152:153], off
	s_waitcnt vmcnt(8) lgkmcnt(0)
	s_barrier
	v_mfma_f32_16x16x128_f8f6f4 v[120:123], v[0:7], v[16:23], v[120:123]
	v_mfma_f32_16x16x128_f8f6f4 v[124:127], v[8:15], v[16:23], v[124:127]
	v_mfma_f32_16x16x128_f8f6f4 v[104:107], v[0:7], v[24:31], v[104:107]
	v_mfma_f32_16x16x128_f8f6f4 v[108:111], v[8:15], v[24:31], v[108:111]
	v_mfma_f32_16x16x128_f8f6f4 v[96:99], v[0:7], v[36:43], v[96:99]
	v_mfma_f32_16x16x128_f8f6f4 v[100:103], v[8:15], v[36:43], v[100:103]
	v_mfma_f32_16x16x128_f8f6f4 v[80:83], v[0:7], v[144:151], v[80:83]
	v_mfma_f32_16x16x128_f8f6f4 v[84:87], v[8:15], v[144:151], v[84:87]
	v_mfma_f32_16x16x128_f8f6f4 v[112:115], v[128:135], v[16:23], v[112:115]
	v_mfma_f32_16x16x128_f8f6f4 v[116:119], v[136:143], v[16:23], v[116:119]
	v_mfma_f32_16x16x128_f8f6f4 v[88:91], v[128:135], v[24:31], v[88:91]
	v_mfma_f32_16x16x128_f8f6f4 v[92:95], v[136:143], v[24:31], v[92:95]
	v_mfma_f32_16x16x128_f8f6f4 v[72:75], v[128:135], v[36:43], v[72:75]
	v_mfma_f32_16x16x128_f8f6f4 v[76:79], v[136:143], v[36:43], v[76:79]
	v_mfma_f32_16x16x128_f8f6f4 v[64:67], v[128:135], v[144:151], v[64:67]
	v_mfma_f32_16x16x128_f8f6f4 v[68:71], v[136:143], v[144:151], v[68:71]
	s_barrier
	s_add_i32 s38, s42, s53
	v_lshl_add_u64 v[16:17], v[160:161], 0, s[14:15]
	s_mov_b32 m0, s38
	ds_read_b128 v[24:27], v220 offset:49152
	ds_read_b128 v[28:31], v220 offset:50176
	ds_read_b128 v[144:147], v220 offset:51200
	ds_read_b128 v[148:151], v220 offset:52224
	ds_read_b128 v[152:155], v220 offset:53248
	ds_read_b128 v[156:159], v220 offset:54272
	ds_read_b128 v[168:171], v220 offset:55296
	ds_read_b128 v[172:175], v220 offset:56320
	global_load_lds_dwordx4 v[16:17], off
	s_add_i32 m0, s38, 0x2000
	s_add_u32 s36, s36, 0x40080
	v_lshl_add_u64 v[16:17], v[162:163], 0, s[14:15]
	s_addc_u32 s37, s37, 0
	s_add_i32 s38, s43, s53
	global_load_lds_dwordx4 v[16:17], off
	v_lshl_add_u64 v[16:17], s[36:37], 0, v[188:189]
	s_mov_b32 m0, s38
	s_nop 0
	global_load_lds_dwordx4 v[16:17], off
	v_lshl_add_u64 v[16:17], s[36:37], 0, v[184:185]
	s_add_i32 m0, s38, 0x2000
	s_nop 0
	global_load_lds_dwordx4 v[16:17], off
	v_lshl_add_u64 v[16:17], v[164:165], 0, s[14:15]
	s_mov_b32 m0, s71
	s_nop 0
	global_load_lds_dwordx4 v[16:17], off
	v_lshl_add_u64 v[16:17], v[166:167], 0, s[14:15]
	s_mov_b32 m0, s72
	s_nop 0
	global_load_lds_dwordx4 v[16:17], off
	s_waitcnt vmcnt(8) lgkmcnt(0)
	s_barrier
	v_mfma_f32_16x16x128_f8f6f4 v[56:59], v[0:7], v[24:31], v[56:59]
	v_mfma_f32_16x16x128_f8f6f4 v[60:63], v[8:15], v[24:31], v[60:63]
	v_mfma_f32_16x16x128_f8f6f4 v[48:51], v[0:7], v[144:151], v[48:51]
	v_mfma_f32_16x16x128_f8f6f4 v[52:55], v[8:15], v[144:151], v[52:55]
	v_mfma_f32_16x16x128_f8f6f4 v[32:35], v[0:7], v[152:159], v[32:35]
	v_mfma_f32_16x16x128_f8f6f4 v[36:39], v[8:15], v[152:159], v[212:215]
	v_mfma_f32_16x16x128_f8f6f4 v[16:19], v[0:7], v[168:175], v[230:233]
	v_mfma_f32_16x16x128_f8f6f4 v[20:23], v[8:15], v[168:175], v[234:237]
	v_mfma_f32_16x16x128_f8f6f4 v[40:43], v[128:135], v[24:31], v[238:241]
	v_mfma_f32_16x16x128_f8f6f4 v[44:47], v[136:143], v[24:31], v[44:47]
	v_mfma_f32_16x16x128_f8f6f4 v[24:27], v[128:135], v[144:151], v[242:245]
	v_mfma_f32_16x16x128_f8f6f4 v[28:31], v[136:143], v[144:151], v[176:179]
	v_mfma_f32_16x16x128_f8f6f4 v[8:11], v[128:135], v[152:159], v[180:183]
	v_mfma_f32_16x16x128_f8f6f4 v[12:15], v[136:143], v[152:159], v[204:207]
	v_mfma_f32_16x16x128_f8f6f4 v[0:3], v[128:135], v[168:175], v[208:211]
	v_mfma_f32_16x16x128_f8f6f4 v[4:7], v[136:143], v[168:175], v[222:225]
	s_barrier
	s_add_u32 s34, s34, 0x100
	s_addc_u32 s35, s35, 0
	s_add_u32 s89, s89, 0x100
	s_addc_u32 s90, s90, 0
	s_cmp_ge_u32 s3, s29
	s_mov_b32 s38, s3
	s_cbranch_scc0 .LBB0_2290
	s_and_b64 vcc, exec, s[12:13]
	s_cbranch_vccz .LBB0_2293
	s_barrier

; #define PG8_STAGE(bufoff, gbase, voff) do { _Pragma("unroll") for (int _i = 0; _i < 2; ++_i) \
;         __builtin_amdgcn_global_load_lds((const unsigned*)((const char*)(gbase) + (voff)[_i]), (LAS unsigned*)(lds + (bufoff) + ldsw + _i * 8192), 16, 0, 0); } while (0)
; #define PG8_LDA(dst, b, h) do { _Pragma("unroll") for (int m = 0; m < 4; ++m) _Pragma("unroll") for (int k = 0; k < 2; ++k) dst[m][k] = *(const LAS bf16x8*)(lds + PG8_SA(b, h) + aoff + m * 2048 + k * KOFF); } while (0)
; #define PG8_LDB(dst, b, h) do { _Pragma("unroll") for (int n = 0; n < 2; ++n) _Pragma("unroll") for (int k = 0; k < 2; ++k) dst[n][k] = *(const LAS bf16x8*)(lds + PG8_SB(b, h) + boff + n * 2048 + k * KOFF); } while (0)
; #define PG8_WAIT_V(n) asm volatile("s_waitcnt vmcnt(" #n ")" ::: "memory")
; #define PG8_WAIT_L(n) asm volatile("s_waitcnt lgkmcnt(" #n ")" ::: "memory")
; #define PG8_BAR __builtin_amdgcn_s_barrier()
; #define PG8_SCHED __builtin_amdgcn_sched_barrier(0)
; template <class Epi, bool ALIGN_EPI = true, bool FP8 = false>
; __device__ __forceinline__ void gemm_phase(LAS unsigned char* lds, const Gemm g, const StaticOrder& S, const Epi& E, const int wid) {
;     ...
;             const char* a1 = cA + (size_t)(t + 1) * kstep;
;             const char* a2 = last ? nA : cA + (size_t)(t + 2) * kstep; const char* b2 = last ? nB : cB + (size_t)(t + 2) * kstep;
;             const char* a3 = a2 + kstep; const char* b3 = b2 + kstep;
;             PG8_LDB(B0, 0, 0); PG8_LDB(B1, 0, 1); PG8_SCHED; PG8_LDA(At, 0, 0); PG8_STAGE(PG8_SA(1, 1), a1 + hstep, voffA);
;             PG8_WAIT_V(8); PG8_WAIT_L(0); PG8_BAR; PG8_MMA(0, 0, At, B0); PG8_MMA(0, 1, At, B1); PG8_BAR; PG8_SCHED;
;             PG8_LDA(At, 0, 1); PG8_STAGE(PG8_SB(0, 0), b2, voffB); PG8_STAGE(PG8_SB(0, 1), b2 + hstep, voffB); PG8_STAGE(PG8_SA(0, 0), a2, voffA);
;             PG8_WAIT_V(8); PG8_WAIT_L(0); PG8_BAR; PG8_MMA(1, 0, At, B0); PG8_MMA(1, 1, At, B1); PG8_BAR; PG8_SCHED;
.LBB0_2452:
	ds_read_b128 v[152:155], v148
	ds_read_b128 v[156:159], v148 offset:1024
	ds_read_b128 v[160:163], v148 offset:2048
	ds_read_b128 v[164:167], v148 offset:3072
	ds_read_b128 v[168:171], v149
	ds_read_b128 v[172:175], v149 offset:1024
	ds_read_b128 v[176:179], v149 offset:2048
	ds_read_b128 v[180:183], v149 offset:3072
	s_add_i32 s76, s30, 2
	s_add_u32 s31, s28, 0xfff80080
	s_addc_u32 s34, s29, -1
	s_cmp_eq_u32 s43, s30
	s_cselect_b32 s30, s42, s52
	s_cselect_b32 s35, s3, s34
	s_cselect_b32 s34, s17, s31
	s_cselect_b32 s31, s19, s75
	v_lshl_add_u64 v[144:145], s[28:29], 0, v[138:139]
	s_add_i32 m0, s25, 0xc000
	ds_read_b128 v[184:187], v150
	ds_read_b128 v[188:191], v150 offset:1024
	ds_read_b128 v[192:195], v150 offset:2048
	ds_read_b128 v[196:199], v150 offset:3072
	ds_read_b128 v[200:203], v150 offset:4096
	ds_read_b128 v[204:207], v150 offset:5120
	ds_read_b128 v[208:211], v150 offset:6144
	ds_read_b128 v[212:215], v150 offset:7168
	global_load_lds_dwordx4 v[144:145], off
	v_lshl_add_u64 v[144:145], s[28:29], 0, v[140:141]
	s_add_i32 m0, s25, 0xe000
	s_nop 0
	global_load_lds_dwordx4 v[144:145], off
	s_waitcnt vmcnt(8) lgkmcnt(0)
	s_barrier
	v_mfma_f32_16x16x32_bf16 v[124:127], v[152:155], v[184:187], v[124:127]
	v_mfma_f32_16x16x32_bf16 v[116:119], v[160:163], v[184:187], v[116:119]
	v_mfma_f32_16x16x32_bf16 v[108:111], v[152:155], v[192:195], v[108:111]
	v_mfma_f32_16x16x32_bf16 v[100:103], v[160:163], v[192:195], v[100:103]
	v_mfma_f32_16x16x32_bf16 v[92:95], v[152:155], v[200:203], v[92:95]
	v_mfma_f32_16x16x32_bf16 v[84:87], v[160:163], v[200:203], v[84:87]
	v_mfma_f32_16x16x32_bf16 v[76:79], v[152:155], v[208:211], v[76:79]
	v_mfma_f32_16x16x32_bf16 v[68:71], v[160:163], v[208:211], v[68:71]
	v_mfma_f32_16x16x32_bf16 v[124:127], v[156:159], v[188:191], v[124:127]
	v_mfma_f32_16x16x32_bf16 v[116:119], v[164:167], v[188:191], v[116:119]
	v_mfma_f32_16x16x32_bf16 v[108:111], v[156:159], v[196:199], v[108:111]
	v_mfma_f32_16x16x32_bf16 v[100:103], v[164:167], v[196:199], v[100:103]
	v_mfma_f32_16x16x32_bf16 v[92:95], v[156:159], v[204:207], v[92:95]
	v_mfma_f32_16x16x32_bf16 v[84:87], v[164:167], v[204:207], v[84:87]
	v_mfma_f32_16x16x32_bf16 v[76:79], v[156:159], v[212:215], v[76:79]
	v_mfma_f32_16x16x32_bf16 v[68:71], v[164:167], v[212:215], v[68:71]
	v_mfma_f32_16x16x32_bf16 v[120:123], v[168:171], v[184:187], v[120:123]
	v_mfma_f32_16x16x32_bf16 v[112:115], v[176:179], v[184:187], v[112:115]
	v_mfma_f32_16x16x32_bf16 v[104:107], v[168:171], v[192:195], v[104:107]
	v_mfma_f32_16x16x32_bf16 v[96:99], v[176:179], v[192:195], v[96:99]
	v_mfma_f32_16x16x32_bf16 v[88:91], v[168:171], v[200:203], v[88:91]
	v_mfma_f32_16x16x32_bf16 v[80:83], v[176:179], v[200:203], v[80:83]
	v_mfma_f32_16x16x32_bf16 v[72:75], v[168:171], v[208:211], v[72:75]
	v_mfma_f32_16x16x32_bf16 v[64:67], v[176:179], v[208:211], v[64:67]
	v_mfma_f32_16x16x32_bf16 v[120:123], v[172:175], v[188:191], v[120:123]
	v_mfma_f32_16x16x32_bf16 v[112:115], v[180:183], v[188:191], v[112:115]
	v_mfma_f32_16x16x32_bf16 v[104:107], v[172:175], v[196:199], v[104:107]
	v_mfma_f32_16x16x32_bf16 v[96:99], v[180:183], v[196:199], v[96:99]
	v_mfma_f32_16x16x32_bf16 v[88:91], v[172:175], v[204:207], v[88:91]
	v_mfma_f32_16x16x32_bf16 v[80:83], v[180:183], v[204:207], v[80:83]
	v_mfma_f32_16x16x32_bf16 v[72:75], v[172:175], v[212:215], v[72:75]
	v_mfma_f32_16x16x32_bf16 v[64:67], v[180:183], v[212:215], v[64:67]
	s_barrier
	s_add_i32 s77, s65, s38
	v_lshl_add_u64 v[144:145], s[30:31], 0, v[132:133]
	s_mov_b32 m0, s77
	ds_read_b128 v[184:187], v150 offset:16384
	ds_read_b128 v[188:191], v150 offset:17408
	ds_read_b128 v[192:195], v150 offset:18432
	ds_read_b128 v[196:199], v150 offset:19456
	ds_read_b128 v[200:203], v150 offset:20480
	ds_read_b128 v[204:207], v150 offset:21504
	ds_read_b128 v[208:211], v150 offset:22528
	ds_read_b128 v[212:215], v150 offset:23552
	global_load_lds_dwordx4 v[144:145], off
	s_add_i32 m0, s77, 0x2000
	s_add_u32 s78, s30, 0x80000
	v_lshl_add_u64 v[216:217], s[30:31], 0, v[128:129]
	s_addc_u32 s79, s31, 0
	s_add_i32 s77, s66, s38
	global_load_lds_dwordx4 v[216:217], off
	v_lshl_add_u64 v[218:219], s[78:79], 0, v[132:133]
	s_mov_b32 m0, s77
	v_lshl_add_u64 v[220:221], s[34:35], 0, v[130:131]
	global_load_lds_dwordx4 v[218:219], off
	v_lshl_add_u64 v[218:219], s[78:79], 0, v[128:129]
	s_add_i32 m0, s77, 0x2000
	s_nop 0
	global_load_lds_dwordx4 v[218:219], off
	v_lshl_add_u64 v[218:219], s[34:35], 0, v[134:135]
	s_mov_b32 m0, s25
	s_nop 0
	global_load_lds_dwordx4 v[218:219], off
	s_mov_b32 m0, s27
	s_nop 0
	global_load_lds_dwordx4 v[220:221], off
	s_waitcnt vmcnt(8) lgkmcnt(0)
	s_barrier
; #define PG8_STAGE(bufoff, gbase, voff) do { _Pragma("unroll") for (int _i = 0; _i < 2; ++_i) \
;         __builtin_amdgcn_global_load_lds((const unsigned*)((const char*)(gbase) + (voff)[_i]), (LAS unsigned*)(lds + (bufoff) + ldsw + _i * 8192), 16, 0, 0); } while (0)
; #define PG8_LDA(dst, b, h) do { _Pragma("unroll") for (int m = 0; m < 4; ++m) _Pragma("unroll") for (int k = 0; k < 2; ++k) dst[m][k] = *(const LAS bf16x8*)(lds + PG8_SA(b, h) + aoff + m * 2048 + k * KOFF); } while (0)
; #define PG8_LDB(dst, b, h) do { _Pragma("unroll") for (int n = 0; n < 2; ++n) _Pragma("unroll") for (int k = 0; k < 2; ++k) dst[n][k] = *(const LAS bf16x8*)(lds + PG8_SB(b, h) + boff + n * 2048 + k * KOFF); } while (0)
; #define PG8_WAIT_V(n) asm volatile("s_waitcnt vmcnt(" #n ")" ::: "memory")
; #define PG8_WAIT_L(n) asm volatile("s_waitcnt lgkmcnt(" #n ")" ::: "memory")
; #define PG8_BAR __builtin_amdgcn_s_barrier()
; #define PG8_SCHED __builtin_amdgcn_sched_barrier(0)
; template <class Epi, bool ALIGN_EPI = true, bool FP8 = false>
; __device__ __forceinline__ void gemm_phase(LAS unsigned char* lds, const Gemm g, const StaticOrder& S, const Epi& E, const int wid) {
;     ...
;             PG8_WAIT_V(8); PG8_WAIT_L(0); PG8_BAR; PG8_MMA(1, 0, At, B0); PG8_MMA(1, 1, At, B1); PG8_BAR; PG8_SCHED;
;             PG8_LDB(B0, 1, 0); PG8_LDB(B1, 1, 1); PG8_SCHED; PG8_LDA(At, 1, 0); PG8_STAGE(PG8_SA(0, 1), a2 + hstep, voffA);
;             PG8_WAIT_V(8); PG8_WAIT_L(0); PG8_BAR; PG8_MMA(0, 0, At, B0); PG8_MMA(0, 1, At, B1); PG8_BAR; PG8_SCHED;
	v_mfma_f32_16x16x32_bf16 v[60:63], v[152:155], v[184:187], v[60:63]
	v_mfma_f32_16x16x32_bf16 v[52:55], v[160:163], v[184:187], v[52:55]
	v_mfma_f32_16x16x32_bf16 v[44:47], v[152:155], v[192:195], v[44:47]
	v_mfma_f32_16x16x32_bf16 v[36:39], v[160:163], v[192:195], v[36:39]
	v_mfma_f32_16x16x32_bf16 v[28:31], v[152:155], v[200:203], v[28:31]
	v_mfma_f32_16x16x32_bf16 v[20:23], v[160:163], v[200:203], v[20:23]
	v_mfma_f32_16x16x32_bf16 v[12:15], v[152:155], v[208:211], v[12:15]
	v_mfma_f32_16x16x32_bf16 v[4:7], v[160:163], v[208:211], v[4:7]
	v_mfma_f32_16x16x32_bf16 v[60:63], v[156:159], v[188:191], v[60:63]
	v_mfma_f32_16x16x32_bf16 v[52:55], v[164:167], v[188:191], v[52:55]
	v_mfma_f32_16x16x32_bf16 v[44:47], v[156:159], v[196:199], v[44:47]
	v_mfma_f32_16x16x32_bf16 v[36:39], v[164:167], v[196:199], v[36:39]
	v_mfma_f32_16x16x32_bf16 v[28:31], v[156:159], v[204:207], v[28:31]
	v_mfma_f32_16x16x32_bf16 v[20:23], v[164:167], v[204:207], v[20:23]
	v_mfma_f32_16x16x32_bf16 v[12:15], v[156:159], v[212:215], v[12:15]
	v_mfma_f32_16x16x32_bf16 v[4:7], v[164:167], v[212:215], v[4:7]
	v_mfma_f32_16x16x32_bf16 v[56:59], v[168:171], v[184:187], v[56:59]
	v_mfma_f32_16x16x32_bf16 v[48:51], v[176:179], v[184:187], v[48:51]
	v_mfma_f32_16x16x32_bf16 v[40:43], v[168:171], v[192:195], v[40:43]
	v_mfma_f32_16x16x32_bf16 v[32:35], v[176:179], v[192:195], v[32:35]
	v_mfma_f32_16x16x32_bf16 v[24:27], v[168:171], v[200:203], v[24:27]
	v_mfma_f32_16x16x32_bf16 v[16:19], v[176:179], v[200:203], v[16:19]
	v_mfma_f32_16x16x32_bf16 v[8:11], v[168:171], v[208:211], v[8:11]
	v_mfma_f32_16x16x32_bf16 v[0:3], v[176:179], v[208:211], v[0:3]
	v_mfma_f32_16x16x32_bf16 v[56:59], v[172:175], v[188:191], v[56:59]
	v_mfma_f32_16x16x32_bf16 v[48:51], v[180:183], v[188:191], v[48:51]
	v_mfma_f32_16x16x32_bf16 v[40:43], v[172:175], v[196:199], v[40:43]
	v_mfma_f32_16x16x32_bf16 v[32:35], v[180:183], v[196:199], v[32:35]
	v_mfma_f32_16x16x32_bf16 v[24:27], v[172:175], v[204:207], v[24:27]
	v_mfma_f32_16x16x32_bf16 v[16:19], v[180:183], v[204:207], v[16:19]
	v_mfma_f32_16x16x32_bf16 v[8:11], v[172:175], v[212:215], v[8:11]
	v_mfma_f32_16x16x32_bf16 v[0:3], v[180:183], v[212:215], v[0:3]
	s_barrier
	s_add_i32 s77, 0, 0x18000
	s_add_i32 s78, 0, 0x1c000
	v_add_u32_e32 v164, s77, v147
	v_add_u32_e32 v180, s78, v147
	ds_read_b128 v[152:155], v164
	ds_read_b128 v[156:159], v164 offset:1024
	ds_read_b128 v[160:163], v164 offset:2048
	ds_read_b128 v[164:167], v164 offset:3072
	ds_read_b128 v[168:171], v180
	ds_read_b128 v[172:175], v180 offset:1024
	ds_read_b128 v[176:179], v180 offset:2048
	ds_read_b128 v[180:183], v180 offset:3072
	s_add_u32 s34, s34, 0x80000
	s_addc_u32 s35, s35, 0
	s_mov_b32 m0, s39
	v_lshl_add_u64 v[222:223], s[34:35], 0, v[134:135]
	ds_read_b128 v[184:187], v150 offset:32768
	ds_read_b128 v[188:191], v150 offset:33792
	ds_read_b128 v[192:195], v150 offset:34816
	ds_read_b128 v[196:199], v150 offset:35840
	ds_read_b128 v[200:203], v150 offset:36864
	ds_read_b128 v[204:207], v150 offset:37888
	ds_read_b128 v[208:211], v150 offset:38912
	ds_read_b128 v[212:215], v150 offset:39936
	global_load_lds_dwordx4 v[222:223], off
	v_lshl_add_u64 v[222:223], s[34:35], 0, v[130:131]
	s_mov_b32 m0, s48
	s_nop 0
	global_load_lds_dwordx4 v[222:223], off
	s_waitcnt vmcnt(8) lgkmcnt(0)
	s_barrier
	v_mfma_f32_16x16x32_bf16 v[124:127], v[152:155], v[184:187], v[124:127]
	v_mfma_f32_16x16x32_bf16 v[116:119], v[160:163], v[184:187], v[116:119]
	v_mfma_f32_16x16x32_bf16 v[108:111], v[152:155], v[192:195], v[108:111]
	v_mfma_f32_16x16x32_bf16 v[100:103], v[160:163], v[192:195], v[100:103]
	v_mfma_f32_16x16x32_bf16 v[92:95], v[152:155], v[200:203], v[92:95]
	v_mfma_f32_16x16x32_bf16 v[84:87], v[160:163], v[200:203], v[84:87]
	v_mfma_f32_16x16x32_bf16 v[76:79], v[152:155], v[208:211], v[76:79]
	v_mfma_f32_16x16x32_bf16 v[68:71], v[160:163], v[208:211], v[68:71]
	v_mfma_f32_16x16x32_bf16 v[124:127], v[156:159], v[188:191], v[124:127]
	v_mfma_f32_16x16x32_bf16 v[116:119], v[164:167], v[188:191], v[116:119]
	v_mfma_f32_16x16x32_bf16 v[108:111], v[156:159], v[196:199], v[108:111]
	v_mfma_f32_16x16x32_bf16 v[100:103], v[164:167], v[196:199], v[100:103]
	v_mfma_f32_16x16x32_bf16 v[92:95], v[156:159], v[204:207], v[92:95]
	v_mfma_f32_16x16x32_bf16 v[84:87], v[164:167], v[204:207], v[84:87]
	v_mfma_f32_16x16x32_bf16 v[76:79], v[156:159], v[212:215], v[76:79]
	v_mfma_f32_16x16x32_bf16 v[68:71], v[164:167], v[212:215], v[68:71]
	v_mfma_f32_16x16x32_bf16 v[120:123], v[168:171], v[184:187], v[120:123]
	v_mfma_f32_16x16x32_bf16 v[112:115], v[176:179], v[184:187], v[112:115]
	v_mfma_f32_16x16x32_bf16 v[104:107], v[168:171], v[192:195], v[104:107]
	v_mfma_f32_16x16x32_bf16 v[96:99], v[176:179], v[192:195], v[96:99]
	v_mfma_f32_16x16x32_bf16 v[88:91], v[168:171], v[200:203], v[88:91]
	v_mfma_f32_16x16x32_bf16 v[80:83], v[176:179], v[200:203], v[80:83]
	v_mfma_f32_16x16x32_bf16 v[72:75], v[168:171], v[208:211], v[72:75]
	v_mfma_f32_16x16x32_bf16 v[64:67], v[176:179], v[208:211], v[64:67]
	v_mfma_f32_16x16x32_bf16 v[120:123], v[172:175], v[188:191], v[120:123]
	v_mfma_f32_16x16x32_bf16 v[112:115], v[180:183], v[188:191], v[112:115]
	v_mfma_f32_16x16x32_bf16 v[104:107], v[172:175], v[196:199], v[104:107]
	v_mfma_f32_16x16x32_bf16 v[96:99], v[180:183], v[196:199], v[96:99]
	v_mfma_f32_16x16x32_bf16 v[88:91], v[172:175], v[204:207], v[88:91]
	v_mfma_f32_16x16x32_bf16 v[80:83], v[180:183], v[204:207], v[80:83]
	v_mfma_f32_16x16x32_bf16 v[72:75], v[172:175], v[212:215], v[72:75]
	v_mfma_f32_16x16x32_bf16 v[64:67], v[180:183], v[212:215], v[64:67]
	s_barrier
; #define PG8_STAGE(bufoff, gbase, voff) do { _Pragma("unroll") for (int _i = 0; _i < 2; ++_i) \
;         __builtin_amdgcn_global_load_lds((const unsigned*)((const char*)(gbase) + (voff)[_i]), (LAS unsigned*)(lds + (bufoff) + ldsw + _i * 8192), 16, 0, 0); } while (0)
; #define PG8_LDA(dst, b, h) do { _Pragma("unroll") for (int m = 0; m < 4; ++m) _Pragma("unroll") for (int k = 0; k < 2; ++k) dst[m][k] = *(const LAS bf16x8*)(lds + PG8_SA(b, h) + aoff + m * 2048 + k * KOFF); } while (0)
; #define PG8_WAIT_V(n) asm volatile("s_waitcnt vmcnt(" #n ")" ::: "memory")
; #define PG8_WAIT_L(n) asm volatile("s_waitcnt lgkmcnt(" #n ")" ::: "memory")
; #define PG8_BAR __builtin_amdgcn_s_barrier()
; #define PG8_SCHED __builtin_amdgcn_sched_barrier(0)
; template <class Epi, bool ALIGN_EPI = true, bool FP8 = false>
; __device__ __forceinline__ void gemm_phase(LAS unsigned char* lds, const Gemm g, const StaticOrder& S, const Epi& E, const int wid) {
;     ...
;             PG8_LDA(At, 1, 1); PG8_STAGE(PG8_SB(1, 0), b3, voffB); PG8_STAGE(PG8_SB(1, 1), b3 + hstep, voffB); PG8_STAGE(PG8_SA(1, 0), a3, voffA);
;             PG8_WAIT_V(8); PG8_WAIT_L(0); PG8_BAR; PG8_MMA(1, 0, At, B0); PG8_MMA(1, 1, At, B1); PG8_BAR; PG8_SCHED;
;         }
	s_add_i32 s34, s77, s38
	v_lshl_add_u64 v[144:145], v[144:145], 0, s[14:15]
	s_mov_b32 m0, s34
	ds_read_b128 v[184:187], v150 offset:49152
	ds_read_b128 v[188:191], v150 offset:50176
	ds_read_b128 v[192:195], v150 offset:51200
	ds_read_b128 v[196:199], v150 offset:52224
	ds_read_b128 v[200:203], v150 offset:53248
	ds_read_b128 v[204:207], v150 offset:54272
	ds_read_b128 v[208:211], v150 offset:55296
	ds_read_b128 v[212:215], v150 offset:56320
	global_load_lds_dwordx4 v[144:145], off
	s_add_i32 m0, s34, 0x2000
	s_add_u32 s30, s30, 0x80080
	v_lshl_add_u64 v[144:145], v[216:217], 0, s[14:15]
	s_addc_u32 s31, s31, 0
	s_add_i32 s34, s78, s38
	global_load_lds_dwordx4 v[144:145], off
	v_lshl_add_u64 v[144:145], s[30:31], 0, v[132:133]
	s_mov_b32 m0, s34
	s_nop 0
	global_load_lds_dwordx4 v[144:145], off
	v_lshl_add_u64 v[144:145], s[30:31], 0, v[128:129]
	s_add_i32 m0, s34, 0x2000
	s_nop 0
	global_load_lds_dwordx4 v[144:145], off
	v_lshl_add_u64 v[144:145], v[218:219], 0, s[14:15]
	s_mov_b32 m0, s53
	s_nop 0
	global_load_lds_dwordx4 v[144:145], off
	v_lshl_add_u64 v[144:145], v[220:221], 0, s[14:15]
	s_mov_b32 m0, s55
	s_nop 0
	global_load_lds_dwordx4 v[144:145], off
	s_waitcnt vmcnt(8) lgkmcnt(0)
	s_barrier
	v_mfma_f32_16x16x32_bf16 v[60:63], v[152:155], v[184:187], v[60:63]
	v_mfma_f32_16x16x32_bf16 v[52:55], v[160:163], v[184:187], v[52:55]
	v_mfma_f32_16x16x32_bf16 v[44:47], v[152:155], v[192:195], v[44:47]
	v_mfma_f32_16x16x32_bf16 v[36:39], v[160:163], v[192:195], v[36:39]
	v_mfma_f32_16x16x32_bf16 v[28:31], v[152:155], v[200:203], v[28:31]
	v_mfma_f32_16x16x32_bf16 v[20:23], v[160:163], v[200:203], v[20:23]
	v_mfma_f32_16x16x32_bf16 v[12:15], v[152:155], v[208:211], v[12:15]
	v_mfma_f32_16x16x32_bf16 v[4:7], v[160:163], v[208:211], v[4:7]
	v_mfma_f32_16x16x32_bf16 v[60:63], v[156:159], v[188:191], v[60:63]
	v_mfma_f32_16x16x32_bf16 v[52:55], v[164:167], v[188:191], v[52:55]
	v_mfma_f32_16x16x32_bf16 v[44:47], v[156:159], v[196:199], v[44:47]
	v_mfma_f32_16x16x32_bf16 v[36:39], v[164:167], v[196:199], v[36:39]
	v_mfma_f32_16x16x32_bf16 v[28:31], v[156:159], v[204:207], v[28:31]
	v_mfma_f32_16x16x32_bf16 v[20:23], v[164:167], v[204:207], v[20:23]
	v_mfma_f32_16x16x32_bf16 v[12:15], v[156:159], v[212:215], v[12:15]
	v_mfma_f32_16x16x32_bf16 v[4:7], v[164:167], v[212:215], v[4:7]
	v_mfma_f32_16x16x32_bf16 v[56:59], v[168:171], v[184:187], v[56:59]
	v_mfma_f32_16x16x32_bf16 v[48:51], v[176:179], v[184:187], v[48:51]
	v_mfma_f32_16x16x32_bf16 v[40:43], v[168:171], v[192:195], v[40:43]
	v_mfma_f32_16x16x32_bf16 v[32:35], v[176:179], v[192:195], v[32:35]
	v_mfma_f32_16x16x32_bf16 v[24:27], v[168:171], v[200:203], v[24:27]
	v_mfma_f32_16x16x32_bf16 v[16:19], v[176:179], v[200:203], v[16:19]
	v_mfma_f32_16x16x32_bf16 v[8:11], v[168:171], v[208:211], v[8:11]
	v_mfma_f32_16x16x32_bf16 v[0:3], v[176:179], v[208:211], v[0:3]
	v_mfma_f32_16x16x32_bf16 v[56:59], v[172:175], v[188:191], v[56:59]
	v_mfma_f32_16x16x32_bf16 v[48:51], v[180:183], v[188:191], v[48:51]
	v_mfma_f32_16x16x32_bf16 v[40:43], v[172:175], v[196:199], v[40:43]
	v_mfma_f32_16x16x32_bf16 v[32:35], v[180:183], v[196:199], v[32:35]
	v_mfma_f32_16x16x32_bf16 v[24:27], v[172:175], v[204:207], v[24:27]
	v_mfma_f32_16x16x32_bf16 v[16:19], v[180:183], v[204:207], v[16:19]
	v_mfma_f32_16x16x32_bf16 v[8:11], v[172:175], v[212:215], v[8:11]
	v_mfma_f32_16x16x32_bf16 v[0:3], v[180:183], v[212:215], v[0:3]
	s_barrier
	s_add_u32 s28, s28, 0x100
	s_addc_u32 s29, s29, 0
	s_add_u32 s52, s52, 0x100
	s_addc_u32 s75, s75, 0
	s_cmp_ge_u32 s76, s54
	s_mov_b32 s30, s76
	s_cbranch_scc0 .LBB0_2452
	s_and_b64 vcc, exec, s[12:13]
	s_cbranch_vccz .LBB0_2455

; #define PG8_STAGE(bufoff, gbase, voff) do { _Pragma("unroll") for (int _i = 0; _i < 2; ++_i) \
;         __builtin_amdgcn_global_load_lds((const unsigned*)((const char*)(gbase) + (voff)[_i]), (LAS unsigned*)(lds + (bufoff) + ldsw + _i * 8192), 16, 0, 0); } while (0)
; #define PG8_LDA(dst, b, h) do { _Pragma("unroll") for (int m = 0; m < 4; ++m) _Pragma("unroll") for (int k = 0; k < 2; ++k) dst[m][k] = *(const LAS bf16x8*)(lds + PG8_SA(b, h) + aoff + m * 2048 + k * KOFF); } while (0)
; #define PG8_LDB(dst, b, h) do { _Pragma("unroll") for (int n = 0; n < 2; ++n) _Pragma("unroll") for (int k = 0; k < 2; ++k) dst[n][k] = *(const LAS bf16x8*)(lds + PG8_SB(b, h) + boff + n * 2048 + k * KOFF); } while (0)
; #define PG8_WAIT_V(n) asm volatile("s_waitcnt vmcnt(" #n ")" ::: "memory")
; #define PG8_WAIT_L(n) asm volatile("s_waitcnt lgkmcnt(" #n ")" ::: "memory")
; #define PG8_BAR __builtin_amdgcn_s_barrier()
; #define PG8_SCHED __builtin_amdgcn_sched_barrier(0)
; template <class Epi, bool ALIGN_EPI = true, bool FP8 = false>
; __device__ __forceinline__ void gemm_phase(LAS unsigned char* lds, const Gemm g, const StaticOrder& S, const Epi& E, const int wid) {
;     ...
;             const char* a1 = cA + (size_t)(t + 1) * kstep;
;             const char* a2 = last ? nA : cA + (size_t)(t + 2) * kstep; const char* b2 = last ? nB : cB + (size_t)(t + 2) * kstep;
;             const char* a3 = a2 + kstep; const char* b3 = b2 + kstep;
;             PG8_LDB(B0, 0, 0); PG8_LDB(B1, 0, 1); PG8_SCHED; PG8_LDA(At, 0, 0); PG8_STAGE(PG8_SA(1, 1), a1 + hstep, voffA);
;             PG8_WAIT_V(8); PG8_WAIT_L(0); PG8_BAR; PG8_MMA(0, 0, At, B0); PG8_MMA(0, 1, At, B1); PG8_BAR; PG8_SCHED;
;             PG8_LDA(At, 0, 1); PG8_STAGE(PG8_SB(0, 0), b2, voffB); PG8_STAGE(PG8_SB(0, 1), b2 + hstep, voffB); PG8_STAGE(PG8_SA(0, 0), a2, voffA);
;             PG8_WAIT_V(8); PG8_WAIT_L(0); PG8_BAR; PG8_MMA(1, 0, At, B0); PG8_MMA(1, 1, At, B1); PG8_BAR; PG8_SCHED;
.LBB0_2536:
	ds_read_b128 v[152:155], v188
	ds_read_b128 v[156:159], v188 offset:1024
	ds_read_b128 v[144:147], v188 offset:2048
	ds_read_b128 v[148:151], v188 offset:3072
	ds_read_b128 v[136:139], v189
	ds_read_b128 v[140:143], v189 offset:1024
	ds_read_b128 v[128:131], v189 offset:2048
	ds_read_b128 v[132:135], v189 offset:3072
	s_add_i32 s42, s26, 2
	s_add_u32 s27, s24, 0xfff50080
	s_addc_u32 s28, s25, -1
	s_cmp_eq_u32 s81, s26
	s_cselect_b32 s26, s20, s82
	s_cselect_b32 s29, s7, s28
	s_cselect_b32 s28, s6, s27
	s_cselect_b32 s27, s21, s83
	v_lshl_add_u64 v[216:217], s[24:25], 0, v[172:173]
	s_add_i32 m0, s34, 0xc000
	ds_read_b128 v[178:181], v190
	ds_read_b128 v[182:185], v190 offset:1024
	ds_read_b128 v[192:195], v190 offset:2048
	ds_read_b128 v[196:199], v190 offset:3072
	ds_read_b128 v[200:203], v190 offset:4096
	ds_read_b128 v[204:207], v190 offset:5120
	ds_read_b128 v[208:211], v190 offset:6144
	ds_read_b128 v[212:215], v190 offset:7168
	global_load_lds_dwordx4 v[216:217], off
	v_lshl_add_u64 v[216:217], s[24:25], 0, v[174:175]
	s_add_i32 m0, s34, 0xe000
	s_nop 0
	global_load_lds_dwordx4 v[216:217], off
	s_waitcnt vmcnt(8) lgkmcnt(0)
	s_barrier
	v_mfma_f32_16x16x128_f8f6f4 v[120:123], v[152:159], v[178:185], v[120:123]
	v_mfma_f32_16x16x128_f8f6f4 v[124:127], v[144:151], v[178:185], v[124:127]
	v_mfma_f32_16x16x128_f8f6f4 v[112:115], v[152:159], v[192:199], v[112:115]
	v_mfma_f32_16x16x128_f8f6f4 v[116:119], v[144:151], v[192:199], v[116:119]
	v_mfma_f32_16x16x128_f8f6f4 v[96:99], v[152:159], v[200:207], v[96:99]
	v_mfma_f32_16x16x128_f8f6f4 v[100:103], v[144:151], v[200:207], v[100:103]
	v_mfma_f32_16x16x128_f8f6f4 v[80:83], v[152:159], v[208:215], v[80:83]
	v_mfma_f32_16x16x128_f8f6f4 v[84:87], v[144:151], v[208:215], v[84:87]
	v_mfma_f32_16x16x128_f8f6f4 v[104:107], v[136:143], v[178:185], v[104:107]
	v_mfma_f32_16x16x128_f8f6f4 v[108:111], v[128:135], v[178:185], v[108:111]
	v_mfma_f32_16x16x128_f8f6f4 v[88:91], v[136:143], v[192:199], v[88:91]
	v_mfma_f32_16x16x128_f8f6f4 v[92:95], v[128:135], v[192:199], v[92:95]
	v_mfma_f32_16x16x128_f8f6f4 v[72:75], v[136:143], v[200:207], v[72:75]
	v_mfma_f32_16x16x128_f8f6f4 v[76:79], v[128:135], v[200:207], v[76:79]
	v_mfma_f32_16x16x128_f8f6f4 v[64:67], v[136:143], v[208:215], v[64:67]
	v_mfma_f32_16x16x128_f8f6f4 v[68:71], v[128:135], v[208:215], v[68:71]
	s_barrier
	s_add_i32 s43, s64, s31
	v_lshl_add_u64 v[178:179], s[26:27], 0, v[162:163]
	s_mov_b32 m0, s43
	ds_read_b128 v[192:195], v190 offset:16384
	ds_read_b128 v[196:199], v190 offset:17408
	ds_read_b128 v[200:203], v190 offset:18432
	ds_read_b128 v[204:207], v190 offset:19456
	ds_read_b128 v[208:211], v190 offset:20480
	ds_read_b128 v[212:215], v190 offset:21504
	ds_read_b128 v[216:219], v190 offset:22528
	ds_read_b128 v[220:223], v190 offset:23552
	global_load_lds_dwordx4 v[178:179], off
	s_add_i32 m0, s43, 0x2000
	s_add_u32 s84, s26, 0xb0000
	v_lshl_add_u64 v[180:181], s[26:27], 0, v[166:167]
	s_addc_u32 s85, s27, 0
	s_add_i32 s43, s65, s31
	global_load_lds_dwordx4 v[180:181], off
	v_lshl_add_u64 v[182:183], s[84:85], 0, v[162:163]
	s_mov_b32 m0, s43
	v_lshl_add_u64 v[184:185], s[28:29], 0, v[164:165]
	global_load_lds_dwordx4 v[182:183], off
	v_lshl_add_u64 v[182:183], s[84:85], 0, v[166:167]
	s_add_i32 m0, s43, 0x2000
	s_nop 0
	global_load_lds_dwordx4 v[182:183], off
	v_lshl_add_u64 v[182:183], s[28:29], 0, v[160:161]
	s_mov_b32 m0, s34
	s_nop 0
	global_load_lds_dwordx4 v[182:183], off
	s_mov_b32 m0, s35
	s_nop 0
	global_load_lds_dwordx4 v[184:185], off
	s_waitcnt vmcnt(8) lgkmcnt(0)
	s_barrier
	v_mfma_f32_16x16x128_f8f6f4 v[56:59], v[152:159], v[192:199], v[56:59]
	v_mfma_f32_16x16x128_f8f6f4 v[60:63], v[144:151], v[192:199], v[60:63]
	v_mfma_f32_16x16x128_f8f6f4 v[48:51], v[152:159], v[200:207], v[48:51]
	v_mfma_f32_16x16x128_f8f6f4 v[52:55], v[144:151], v[200:207], v[52:55]
	v_mfma_f32_16x16x128_f8f6f4 v[32:35], v[152:159], v[208:215], v[32:35]
	v_mfma_f32_16x16x128_f8f6f4 v[224:227], v[144:151], v[208:215], v[36:39]
	v_mfma_f32_16x16x128_f8f6f4 v[228:231], v[152:159], v[216:223], v[16:19]
	v_mfma_f32_16x16x128_f8f6f4 v[232:235], v[144:151], v[216:223], v[20:23]
	v_mfma_f32_16x16x128_f8f6f4 v[44:47], v[128:135], v[192:199], v[44:47]
	v_mfma_f32_16x16x128_f8f6f4 v[236:239], v[136:143], v[192:199], v[40:43]
	v_mfma_f32_16x16x128_f8f6f4 v[240:243], v[136:143], v[200:207], v[24:27]
	v_mfma_f32_16x16x128_f8f6f4 v[200:203], v[128:135], v[200:207], v[28:31]
	v_mfma_f32_16x16x128_f8f6f4 v[204:207], v[136:143], v[208:215], v[8:11]
	v_mfma_f32_16x16x128_f8f6f4 v[208:211], v[128:135], v[208:215], v[12:15]
	v_mfma_f32_16x16x128_f8f6f4 v[212:215], v[136:143], v[216:223], v[0:3]
	v_mfma_f32_16x16x128_f8f6f4 v[216:219], v[128:135], v[216:223], v[4:7]
	s_barrier
; #define PG8_STAGE(bufoff, gbase, voff) do { _Pragma("unroll") for (int _i = 0; _i < 2; ++_i) \
;         __builtin_amdgcn_global_load_lds((const unsigned*)((const char*)(gbase) + (voff)[_i]), (LAS unsigned*)(lds + (bufoff) + ldsw + _i * 8192), 16, 0, 0); } while (0)
; #define PG8_LDA(dst, b, h) do { _Pragma("unroll") for (int m = 0; m < 4; ++m) _Pragma("unroll") for (int k = 0; k < 2; ++k) dst[m][k] = *(const LAS bf16x8*)(lds + PG8_SA(b, h) + aoff + m * 2048 + k * KOFF); } while (0)
; #define PG8_LDB(dst, b, h) do { _Pragma("unroll") for (int n = 0; n < 2; ++n) _Pragma("unroll") for (int k = 0; k < 2; ++k) dst[n][k] = *(const LAS bf16x8*)(lds + PG8_SB(b, h) + boff + n * 2048 + k * KOFF); } while (0)
; #define PG8_WAIT_V(n) asm volatile("s_waitcnt vmcnt(" #n ")" ::: "memory")
; #define PG8_WAIT_L(n) asm volatile("s_waitcnt lgkmcnt(" #n ")" ::: "memory")
; #define PG8_BAR __builtin_amdgcn_s_barrier()
; #define PG8_SCHED __builtin_amdgcn_sched_barrier(0)
; template <class Epi, bool ALIGN_EPI = true, bool FP8 = false>
; __device__ __forceinline__ void gemm_phase(LAS unsigned char* lds, const Gemm g, const StaticOrder& S, const Epi& E, const int wid) {
;     ...
;             PG8_LDB(B0, 1, 0); PG8_LDB(B1, 1, 1); PG8_SCHED; PG8_LDA(At, 1, 0); PG8_STAGE(PG8_SA(0, 1), a2 + hstep, voffA);
;             PG8_WAIT_V(8); PG8_WAIT_L(0); PG8_BAR; PG8_MMA(0, 0, At, B0); PG8_MMA(0, 1, At, B1); PG8_BAR; PG8_SCHED;
;             PG8_LDA(At, 1, 1); PG8_STAGE(PG8_SB(1, 0), b3, voffB); PG8_STAGE(PG8_SB(1, 1), b3 + hstep, voffB); PG8_STAGE(PG8_SA(1, 0), a3, voffA);
;             PG8_WAIT_V(8); PG8_WAIT_L(0); PG8_BAR; PG8_MMA(1, 0, At, B0); PG8_MMA(1, 1, At, B1); PG8_BAR; PG8_SCHED;
;         }
	s_add_i32 s43, 0, 0x18000
	s_add_i32 s54, 0, 0x1c000
	s_nop 0
	v_add_u32_e32 v12, s43, v187
	v_add_u32_e32 v16, s54, v187
	ds_read_b128 v[0:3], v12
	ds_read_b128 v[4:7], v12 offset:1024
	ds_read_b128 v[8:11], v12 offset:2048
	ds_read_b128 v[12:15], v12 offset:3072
	ds_read_b128 v[128:131], v16
	ds_read_b128 v[132:135], v16 offset:1024
	ds_read_b128 v[136:139], v16 offset:2048
	ds_read_b128 v[140:143], v16 offset:3072
	s_add_u32 s28, s28, 0xb0000
	s_addc_u32 s29, s29, 0
	s_mov_b32 m0, s36
	v_lshl_add_u64 v[152:153], s[28:29], 0, v[160:161]
	ds_read_b128 v[16:19], v190 offset:32768
	ds_read_b128 v[20:23], v190 offset:33792
	ds_read_b128 v[24:27], v190 offset:34816
	ds_read_b128 v[28:31], v190 offset:35840
	ds_read_b128 v[36:39], v190 offset:36864
	ds_read_b128 v[40:43], v190 offset:37888
	ds_read_b128 v[144:147], v190 offset:38912
	ds_read_b128 v[148:151], v190 offset:39936
	global_load_lds_dwordx4 v[152:153], off
	v_lshl_add_u64 v[152:153], s[28:29], 0, v[164:165]
	s_mov_b32 m0, s37
	s_nop 0
	global_load_lds_dwordx4 v[152:153], off
	s_waitcnt vmcnt(8) lgkmcnt(0)
	s_barrier
	v_mfma_f32_16x16x128_f8f6f4 v[120:123], v[0:7], v[16:23], v[120:123]
	v_mfma_f32_16x16x128_f8f6f4 v[124:127], v[8:15], v[16:23], v[124:127]
	v_mfma_f32_16x16x128_f8f6f4 v[112:115], v[0:7], v[24:31], v[112:115]
	v_mfma_f32_16x16x128_f8f6f4 v[116:119], v[8:15], v[24:31], v[116:119]
	v_mfma_f32_16x16x128_f8f6f4 v[96:99], v[0:7], v[36:43], v[96:99]
	v_mfma_f32_16x16x128_f8f6f4 v[100:103], v[8:15], v[36:43], v[100:103]
	v_mfma_f32_16x16x128_f8f6f4 v[80:83], v[0:7], v[144:151], v[80:83]
	v_mfma_f32_16x16x128_f8f6f4 v[84:87], v[8:15], v[144:151], v[84:87]
	v_mfma_f32_16x16x128_f8f6f4 v[104:107], v[128:135], v[16:23], v[104:107]
	v_mfma_f32_16x16x128_f8f6f4 v[108:111], v[136:143], v[16:23], v[108:111]
	v_mfma_f32_16x16x128_f8f6f4 v[88:91], v[128:135], v[24:31], v[88:91]
	v_mfma_f32_16x16x128_f8f6f4 v[92:95], v[136:143], v[24:31], v[92:95]
	v_mfma_f32_16x16x128_f8f6f4 v[72:75], v[128:135], v[36:43], v[72:75]
	v_mfma_f32_16x16x128_f8f6f4 v[76:79], v[136:143], v[36:43], v[76:79]
	v_mfma_f32_16x16x128_f8f6f4 v[64:67], v[128:135], v[144:151], v[64:67]
	v_mfma_f32_16x16x128_f8f6f4 v[68:71], v[136:143], v[144:151], v[68:71]
	s_barrier
	s_add_i32 s28, s43, s31
	v_lshl_add_u64 v[16:17], v[178:179], 0, s[14:15]
	s_mov_b32 m0, s28
	ds_read_b128 v[24:27], v190 offset:49152
	ds_read_b128 v[28:31], v190 offset:50176
	ds_read_b128 v[144:147], v190 offset:51200
	ds_read_b128 v[148:151], v190 offset:52224
	ds_read_b128 v[152:155], v190 offset:53248
	ds_read_b128 v[156:159], v190 offset:54272
	ds_read_b128 v[192:195], v190 offset:55296
	ds_read_b128 v[196:199], v190 offset:56320
	global_load_lds_dwordx4 v[16:17], off
	s_add_i32 m0, s28, 0x2000
	s_add_u32 s26, s26, 0xb0080
	v_lshl_add_u64 v[16:17], v[180:181], 0, s[14:15]
	s_addc_u32 s27, s27, 0
	s_add_i32 s28, s54, s31
	global_load_lds_dwordx4 v[16:17], off
	v_lshl_add_u64 v[16:17], s[26:27], 0, v[162:163]
	s_mov_b32 m0, s28
	s_nop 0
	global_load_lds_dwordx4 v[16:17], off
	v_lshl_add_u64 v[16:17], s[26:27], 0, v[166:167]
	s_add_i32 m0, s28, 0x2000
	s_nop 0
	global_load_lds_dwordx4 v[16:17], off
	v_lshl_add_u64 v[16:17], v[182:183], 0, s[14:15]
	s_mov_b32 m0, s52
	s_nop 0
	global_load_lds_dwordx4 v[16:17], off
	v_lshl_add_u64 v[16:17], v[184:185], 0, s[14:15]
	s_mov_b32 m0, s53
	s_nop 0
	global_load_lds_dwordx4 v[16:17], off
	s_waitcnt vmcnt(8) lgkmcnt(0)
	s_barrier
	v_mfma_f32_16x16x128_f8f6f4 v[56:59], v[0:7], v[24:31], v[56:59]
	v_mfma_f32_16x16x128_f8f6f4 v[60:63], v[8:15], v[24:31], v[60:63]
	v_mfma_f32_16x16x128_f8f6f4 v[48:51], v[0:7], v[144:151], v[48:51]
	v_mfma_f32_16x16x128_f8f6f4 v[52:55], v[8:15], v[144:151], v[52:55]
	v_mfma_f32_16x16x128_f8f6f4 v[32:35], v[0:7], v[152:159], v[32:35]
	v_mfma_f32_16x16x128_f8f6f4 v[36:39], v[8:15], v[152:159], v[224:227]
	v_mfma_f32_16x16x128_f8f6f4 v[16:19], v[0:7], v[192:199], v[228:231]
	v_mfma_f32_16x16x128_f8f6f4 v[20:23], v[8:15], v[192:199], v[232:235]
	v_mfma_f32_16x16x128_f8f6f4 v[40:43], v[128:135], v[24:31], v[236:239]
	v_mfma_f32_16x16x128_f8f6f4 v[44:47], v[136:143], v[24:31], v[44:47]
	v_mfma_f32_16x16x128_f8f6f4 v[24:27], v[128:135], v[144:151], v[240:243]
	v_mfma_f32_16x16x128_f8f6f4 v[28:31], v[136:143], v[144:151], v[200:203]
	v_mfma_f32_16x16x128_f8f6f4 v[8:11], v[128:135], v[152:159], v[204:207]
	v_mfma_f32_16x16x128_f8f6f4 v[12:15], v[136:143], v[152:159], v[208:211]
	v_mfma_f32_16x16x128_f8f6f4 v[0:3], v[128:135], v[192:199], v[212:215]
	v_mfma_f32_16x16x128_f8f6f4 v[4:7], v[136:143], v[192:199], v[216:219]
	s_barrier
	s_add_u32 s24, s24, 0x100
	s_addc_u32 s25, s25, 0
	s_add_u32 s82, s82, 0x100
	s_addc_u32 s83, s83, 0
	s_cmp_ge_u32 s42, s80
	s_mov_b32 s26, s42
	s_cbranch_scc0 .LBB0_2536
	s_and_b64 vcc, exec, s[16:17]
	s_cbranch_vccz .LBB0_2539
	s_barrier
